# flash loops: drop the lgkmcnt(0) waits before PV MFMAs that have nothing outstanding (V reads retired by the first wait), s_nop keeps cvt->MFMA distance
# speedup vs baseline: 1.0067x; 1.0067x over previous
; #define MFMA(a, b, c) __builtin_amdgcn_mfma_f32_32x32x16_bf16((a), (b), (c), 0, 0, 0)
;     ...
;   float mc = m * c2;
;   if (MODE == 2) mc = selbit ? mc : 1e30f;
;   const f32x2v c2v = {c2, c2}, mcv = {-mc, -mc};
;   f32x2v rs2 = {0.f, 0.f};
; #pragma unroll
;   for (int ks = 0; ks < 2; ++ks)
; #pragma unroll
;     for (int st = 0; st < 2; ++st) {
;       union { unsigned u[4]; bf16x8 v; } pf;
; #pragma unroll
;       for (int j = 0; j < 4; ++j) {
;         const int i0 = 8 * st + 2 * j;
;         f32x2v t = {S[ks][i0], S[ks][i0 + 1]};
;         t = __builtin_elementwise_fma(t, c2v, mcv);
;         f32x2v pv;
;         if (variant == 1) { pv = t; } else {
;         pv.x = __builtin_amdgcn_exp2f(t.x);
;         pv.y = __builtin_amdgcn_exp2f(t.y);
;         }
;         if (MODE != 0) {
;           if (need_mask) {
;             pv.x = (S[ks][i0] > -1e29f) ? pv.x : 0.f;
;             pv.y = (S[ks][i0 + 1] > -1e29f) ? pv.y : 0.f;
;           }
;         }
;         rs2 += pv;
;         pf.u[j] = __builtin_bit_cast(unsigned, __builtin_convertvector(pv, hwbf16x2));
;       }
; #pragma unroll
;       for (int d = 0; d < DV / 32; ++d) {
;         const char* vp = base + C::KBYTES + (d * 32 + lr) * C::VSTR + (ks * 32 + 16 * st + 4 * lh) * 2;
;         const s16x4 lo = *(const s16x4*)vp, hi = *(const s16x4*)(vp + 16);
;         const bf16x8 vf = __builtin_shufflevector(lo, hi, 0, 1, 2, 3, 4, 5, 6, 7);
;         O[d] = MFMA(vf, pf.v, O[d]);
.LBB0_362:
	s_cmp_eq_u64 s[8:9], 0
	s_cbranch_scc1 .Lfast_mla1
	v_mul_f32_e32 v104, 0xbe16c740, v104
	s_mov_b32 s12, 0x3e16c740
	v_pk_fma_f32 v[118:119], v[50:51], s[12:13], v[104:105] op_sel_hi:[1,0,0]
	v_cmp_lt_f32_e32 vcc, s33, v50
	v_exp_f32_e32 v118, v118
	v_exp_f32_e32 v119, v119
	v_cndmask_b32_e32 v50, 0, v118, vcc
	v_cmp_lt_f32_e32 vcc, s33, v51
	v_cndmask_b32_e64 v126, v118, v50, s[8:9]
	s_nop 0
	v_cndmask_b32_e32 v51, 0, v119, vcc
	v_cndmask_b32_e64 v127, v119, v51, s[8:9]
	v_pk_fma_f32 v[50:51], v[52:53], s[12:13], v[104:105] op_sel_hi:[1,0,0]
	v_cmp_lt_f32_e32 vcc, s33, v52
	v_exp_f32_e32 v50, v50
	v_exp_f32_e32 v51, v51
	v_cvt_pk_bf16_f32 v118, v126, v127
	v_cndmask_b32_e32 v52, 0, v50, vcc
	v_cmp_lt_f32_e32 vcc, s33, v53
	v_cndmask_b32_e64 v128, v50, v52, s[8:9]
	s_nop 0
	v_cndmask_b32_e32 v53, 0, v51, vcc
	v_cndmask_b32_e64 v129, v51, v53, s[8:9]
	v_pk_fma_f32 v[50:51], v[54:55], s[12:13], v[104:105] op_sel_hi:[1,0,0]
	v_cmp_lt_f32_e32 vcc, s33, v54
	v_exp_f32_e32 v50, v50
	v_exp_f32_e32 v51, v51
	v_cvt_pk_bf16_f32 v119, v128, v129
	v_cndmask_b32_e32 v52, 0, v50, vcc
	v_cmp_lt_f32_e32 vcc, s33, v55
	v_cndmask_b32_e64 v130, v50, v52, s[8:9]
	s_nop 0
	v_cndmask_b32_e32 v53, 0, v51, vcc
	v_cndmask_b32_e64 v131, v51, v53, s[8:9]
	v_pk_fma_f32 v[50:51], v[56:57], s[12:13], v[104:105] op_sel_hi:[1,0,0]
	v_cmp_lt_f32_e32 vcc, s33, v56
	v_exp_f32_e32 v50, v50
	v_exp_f32_e32 v51, v51
	v_cvt_pk_bf16_f32 v120, v130, v131
	v_cndmask_b32_e32 v52, 0, v50, vcc
	v_cmp_lt_f32_e32 vcc, s33, v57
	v_cndmask_b32_e64 v56, v50, v52, s[8:9]
	s_nop 0
	v_cndmask_b32_e32 v53, 0, v51, vcc
	v_cndmask_b32_e64 v57, v51, v53, s[8:9]
	v_cvt_pk_bf16_f32 v121, v56, v57
	v_cmp_lt_f32_e32 vcc, s33, v58
	s_waitcnt lgkmcnt(0)
	v_mfma_f32_32x32x16_bf16 v[18:33], v[216:219], v[118:121], v[18:33]
	v_mfma_f32_32x32x16_bf16 v[2:17], v[220:223], v[118:121], v[2:17]
	v_add_f32_e64 v52, v126, 0
	v_add_f32_e64 v53, v127, 0
	v_add_f32_e64 v52, v128, v52
	v_add_f32_e64 v53, v129, v53
	v_add_f32_e64 v52, v130, v52
	v_add_f32_e64 v53, v131, v53
	v_pk_add_f32 v[118:119], v[56:57], v[52:53]
	v_pk_fma_f32 v[52:53], v[58:59], s[12:13], v[104:105] op_sel_hi:[1,0,0]
	s_nop 0
	v_exp_f32_e32 v52, v52
	v_exp_f32_e32 v53, v53
	v_cndmask_b32_e32 v54, 0, v52, vcc
	v_cmp_lt_f32_e32 vcc, s33, v59
	v_cndmask_b32_e64 v120, v52, v54, s[8:9]
	s_nop 0
	v_cndmask_b32_e32 v55, 0, v53, vcc
	v_cndmask_b32_e64 v121, v53, v55, s[8:9]
	v_pk_fma_f32 v[54:55], v[60:61], s[12:13], v[104:105] op_sel_hi:[1,0,0]
	v_cmp_lt_f32_e32 vcc, s33, v60
	v_exp_f32_e32 v53, v54
	v_exp_f32_e32 v54, v55
	v_cvt_pk_bf16_f32 v52, v120, v121
	v_cndmask_b32_e32 v55, 0, v53, vcc
	v_cmp_lt_f32_e32 vcc, s33, v61
	v_cndmask_b32_e64 v60, v53, v55, s[8:9]
	s_nop 0
	v_cndmask_b32_e32 v56, 0, v54, vcc
	v_cndmask_b32_e64 v61, v54, v56, s[8:9]
	v_pk_fma_f32 v[54:55], v[62:63], s[12:13], v[104:105] op_sel_hi:[1,0,0]
	v_cmp_lt_f32_e32 vcc, s33, v62
	v_exp_f32_e32 v54, v54
	v_exp_f32_e32 v55, v55
	v_cvt_pk_bf16_f32 v53, v60, v61
	v_cndmask_b32_e32 v56, 0, v54, vcc
	v_cmp_lt_f32_e32 vcc, s33, v63
	v_cndmask_b32_e64 v62, v54, v56, s[8:9]
	s_nop 0
	v_cndmask_b32_e32 v57, 0, v55, vcc
	v_cndmask_b32_e64 v63, v55, v57, s[8:9]
	v_pk_fma_f32 v[56:57], v[64:65], s[12:13], v[104:105] op_sel_hi:[1,0,0]
	v_cmp_lt_f32_e32 vcc, s33, v64
	v_exp_f32_e32 v55, v56
	v_exp_f32_e32 v56, v57
	v_cvt_pk_bf16_f32 v54, v62, v63
	v_cndmask_b32_e32 v57, 0, v55, vcc
	v_cmp_lt_f32_e32 vcc, s33, v65
	v_cndmask_b32_e64 v64, v55, v57, s[8:9]
	s_nop 0
	v_cndmask_b32_e32 v58, 0, v56, vcc
	v_cndmask_b32_e64 v65, v56, v58, s[8:9]
	v_cvt_pk_bf16_f32 v55, v64, v65
	v_cmp_lt_f32_e32 vcc, s33, v34
	s_nop 0
	v_mfma_f32_32x32x16_bf16 v[18:33], v[224:227], v[52:55], v[18:33]
	v_mfma_f32_32x32x16_bf16 v[2:17], v[228:231], v[52:55], v[2:17]
	v_fma_f32 v54, v34, s12, v104
	v_fma_f32 v55, v35, s12, v104
	v_fma_f32 v56, v36, s12, v104
	v_fma_f32 v57, v37, s12, v104
	v_exp_f32_e32 v54, v54
	v_exp_f32_e32 v55, v55
	v_pk_add_f32 v[52:53], v[120:121], v[118:119]
	v_cndmask_b32_e32 v34, 0, v54, vcc
	v_cmp_lt_f32_e32 vcc, s33, v35
	v_pk_add_f32 v[52:53], v[60:61], v[52:53]
	v_cndmask_b32_e64 v54, v54, v34, s[8:9]
	v_cndmask_b32_e32 v35, 0, v55, vcc
	v_cndmask_b32_e64 v55, v55, v35, s[8:9]
	v_exp_f32_e32 v35, v56
	v_exp_f32_e32 v56, v57
	v_cmp_lt_f32_e32 vcc, s33, v36
	v_cvt_pk_bf16_f32 v34, v54, v55
	v_pk_add_f32 v[52:53], v[62:63], v[52:53]
	v_cndmask_b32_e32 v36, 0, v35, vcc
	v_cmp_lt_f32_e32 vcc, s33, v37
	v_pk_add_f32 v[52:53], v[64:65], v[52:53]
	s_nop 0
	v_cndmask_b32_e32 v37, 0, v56, vcc
	v_cndmask_b32_e64 v57, v56, v37, s[8:9]
	v_cndmask_b32_e64 v56, v35, v36, s[8:9]
	v_pk_fma_f32 v[36:37], v[38:39], s[12:13], v[104:105] op_sel_hi:[1,0,0]
	v_cmp_lt_f32_e32 vcc, s33, v38
	v_exp_f32_e32 v36, v36
	v_exp_f32_e32 v37, v37
	v_cvt_pk_bf16_f32 v35, v56, v57
	v_cndmask_b32_e32 v38, 0, v36, vcc
	v_cmp_lt_f32_e32 vcc, s33, v39
	v_cndmask_b32_e64 v58, v36, v38, s[8:9]
	s_nop 0
	v_cndmask_b32_e32 v39, 0, v37, vcc
	v_cndmask_b32_e64 v59, v37, v39, s[8:9]
	v_pk_fma_f32 v[38:39], v[40:41], s[12:13], v[104:105] op_sel_hi:[1,0,0]
	v_cmp_lt_f32_e32 vcc, s33, v40
	v_exp_f32_e32 v37, v38
	v_exp_f32_e32 v38, v39
	v_cvt_pk_bf16_f32 v36, v58, v59
	v_cndmask_b32_e32 v39, 0, v37, vcc
	v_cmp_lt_f32_e32 vcc, s33, v41
	v_cndmask_b32_e64 v60, v37, v39, s[8:9]
	s_nop 0
	v_cndmask_b32_e32 v40, 0, v38, vcc
	v_cndmask_b32_e64 v61, v38, v40, s[8:9]
	v_cvt_pk_bf16_f32 v37, v60, v61
	v_cmp_lt_f32_e32 vcc, s33, v42
	s_waitcnt lgkmcnt(0)
; #define MFMA(a, b, c) __builtin_amdgcn_mfma_f32_32x32x16_bf16((a), (b), (c), 0, 0, 0)
; template <int N> DI void wait_vmcnt() { asm volatile("s_waitcnt vmcnt(%0)" ::"n"(N) : "memory"); }
;     ...
; #pragma unroll
;   for (int ks = 0; ks < 2; ++ks)
; #pragma unroll
;     for (int st = 0; st < 2; ++st) {
;       union { unsigned u[4]; bf16x8 v; } pf;
; #pragma unroll
;       for (int j = 0; j < 4; ++j) {
;         const int i0 = 8 * st + 2 * j;
;         f32x2v t = {S[ks][i0], S[ks][i0 + 1]};
;         t = __builtin_elementwise_fma(t, c2v, mcv);
;         f32x2v pv;
;         if (variant == 1) { pv = t; } else {
;         pv.x = __builtin_amdgcn_exp2f(t.x);
;         pv.y = __builtin_amdgcn_exp2f(t.y);
;         }
;         if (MODE != 0) {
;           if (need_mask) {
;             pv.x = (S[ks][i0] > -1e29f) ? pv.x : 0.f;
;             pv.y = (S[ks][i0 + 1] > -1e29f) ? pv.y : 0.f;
;           }
;         }
;         rs2 += pv;
;         pf.u[j] = __builtin_bit_cast(unsigned, __builtin_convertvector(pv, hwbf16x2));
;       }
; #pragma unroll
;       for (int d = 0; d < DV / 32; ++d) {
;         const char* vp = base + C::KBYTES + (d * 32 + lr) * C::VSTR + (ks * 32 + 16 * st + 4 * lh) * 2;
;         const s16x4 lo = *(const s16x4*)vp, hi = *(const s16x4*)(vp + 16);
;         const bf16x8 vf = __builtin_shufflevector(lo, hi, 0, 1, 2, 3, 4, 5, 6, 7);
;         O[d] = MFMA(vf, pf.v, O[d]);
;       }
;     }
;   float rs = rs2.x + rs2.y;
;   rs += __shfl_xor(rs, 32);
;   l += rs;
;     ...
;   asm volatile("s_waitcnt vmcnt(0)" ::: "memory");
; #pragma unroll
;   for (int t = 0; t < NST - 1; ++t)
;     if (t < ntile) FA_ISSUE(t, t)
;   int stage = 0;
;   for (int t = 0; t < ntile; ++t) {
;     int ahead = ((ntile < t + NST - 1) ? ntile : t + NST - 1) - (t + 1);
;     if (NST == 4 && ahead >= 2) wait_vmcnt<2 * NI>();
;     else if (ahead >= 1) wait_vmcnt<NI>();
;     else wait_vmcnt<0>();
;     raw_barrier();
;     if (t + NST - 1 < ntile) {
;       const int sn = (stage == 0) ? NST - 1 : stage - 1;
;       FA_ISSUE(t + NST - 1, sn)
	v_mfma_f32_32x32x16_bf16 v[18:33], v[232:235], v[34:37], v[18:33]
	v_mfma_f32_32x32x16_bf16 v[2:17], v[236:239], v[34:37], v[2:17]
	v_add_f32_e64 v34, v54, v52
	v_add_f32_e64 v35, v55, v53
	v_add_f32_e64 v34, v56, v34
	v_add_f32_e64 v35, v57, v35
	v_add_f32_e64 v34, v58, v34
	v_add_f32_e64 v35, v59, v35
	v_pk_add_f32 v[52:53], v[60:61], v[34:35]
	v_pk_fma_f32 v[34:35], v[42:43], s[12:13], v[104:105] op_sel_hi:[1,0,0]
	s_nop 0
	v_exp_f32_e32 v34, v34
	v_exp_f32_e32 v35, v35
	v_cndmask_b32_e32 v36, 0, v34, vcc
	v_cmp_lt_f32_e32 vcc, s33, v43
	v_cndmask_b32_e64 v42, v34, v36, s[8:9]
	s_nop 0
	v_cndmask_b32_e32 v37, 0, v35, vcc
	v_cndmask_b32_e64 v43, v35, v37, s[8:9]
	v_pk_fma_f32 v[36:37], v[44:45], s[12:13], v[104:105] op_sel_hi:[1,0,0]
	v_cmp_lt_f32_e32 vcc, s33, v44
	v_exp_f32_e32 v35, v36
	v_exp_f32_e32 v36, v37
	v_cvt_pk_bf16_f32 v34, v42, v43
	v_cndmask_b32_e32 v37, 0, v35, vcc
	v_cmp_lt_f32_e32 vcc, s33, v45
	v_cndmask_b32_e64 v44, v35, v37, s[8:9]
	s_nop 0
	v_cndmask_b32_e32 v38, 0, v36, vcc
	v_cndmask_b32_e64 v45, v36, v38, s[8:9]
	v_pk_fma_f32 v[36:37], v[46:47], s[12:13], v[104:105] op_sel_hi:[1,0,0]
	v_cmp_lt_f32_e32 vcc, s33, v46
	v_exp_f32_e32 v36, v36
	v_exp_f32_e32 v37, v37
	v_cvt_pk_bf16_f32 v35, v44, v45
	v_cndmask_b32_e32 v38, 0, v36, vcc
	v_cmp_lt_f32_e32 vcc, s33, v47
	v_cndmask_b32_e64 v46, v36, v38, s[8:9]
	s_nop 0
	v_cndmask_b32_e32 v39, 0, v37, vcc
	v_cndmask_b32_e64 v47, v37, v39, s[8:9]
	v_pk_fma_f32 v[38:39], v[48:49], s[12:13], v[104:105] op_sel_hi:[1,0,0]
	v_cmp_lt_f32_e32 vcc, s33, v48
	v_exp_f32_e32 v37, v38
	v_exp_f32_e32 v38, v39
	v_cvt_pk_bf16_f32 v36, v46, v47
	v_cndmask_b32_e32 v39, 0, v37, vcc
	v_cmp_lt_f32_e32 vcc, s33, v49
	v_cndmask_b32_e64 v48, v37, v39, s[8:9]
	s_nop 0
	v_cndmask_b32_e32 v40, 0, v38, vcc
	v_cndmask_b32_e64 v49, v38, v40, s[8:9]
	v_cvt_pk_bf16_f32 v37, v48, v49
	s_nop 1
	v_mfma_f32_32x32x16_bf16 v[18:33], v[240:243], v[34:37], v[18:33]
	v_mfma_f32_32x32x16_bf16 v[2:17], v[244:247], v[34:37], v[2:17]
	v_add_f32_e64 v34, v42, v52
	v_add_f32_e64 v35, v43, v53
	v_add_f32_e64 v34, v44, v34
	v_add_f32_e64 v35, v45, v35
	v_add_f32_e64 v34, v46, v34
	v_add_f32_e64 v35, v47, v35
	v_pk_add_f32 v[34:35], v[48:49], v[34:35]
	s_nop 0
	v_add_f32_e32 v34, v34, v35
	ds_bpermute_b32 v35, v117, v34
	s_cmp_ge_u32 s16, s19
	s_cbranch_scc1 .Ldma_m_mla1
	s_add_i32 s98, s6, 0xffffa800
	s_cmp_lg_u32 s22, 0
	s_cselect_b32 s98, s98, 0x10800
	s_add_i32 s98, s98, 0
	v_add_u32_e32 v247, s98, v107
	s_nop 0
	v_readfirstlane_b32 s99, v247
	v_add_u32_e32 v247, s98, v93
	s_mov_b32 m0, s99
	v_readfirstlane_b32 s99, v247
	v_add_u32_e32 v247, s98, v108
	global_load_lds_dwordx4 v[102:103], off
	s_mov_b32 m0, s99
	v_readfirstlane_b32 s98, v247
	global_load_lds_dwordx4 v[100:101], off
	s_mov_b32 m0, s98
	s_nop 0
	global_load_lds_dwordx4 v[98:99], off

; #define MFMA(a, b, c) __builtin_amdgcn_mfma_f32_32x32x16_bf16((a), (b), (c), 0, 0, 0)
; template <int N> DI void wait_vmcnt() { asm volatile("s_waitcnt vmcnt(%0)" ::"n"(N) : "memory"); }
;     ...
;   float mc = m * c2;
;   if (MODE == 2) mc = selbit ? mc : 1e30f;
;   const f32x2v c2v = {c2, c2}, mcv = {-mc, -mc};
;   f32x2v rs2 = {0.f, 0.f};
; #pragma unroll
;   for (int ks = 0; ks < 2; ++ks)
; #pragma unroll
;     for (int st = 0; st < 2; ++st) {
;       union { unsigned u[4]; bf16x8 v; } pf;
; #pragma unroll
;       for (int j = 0; j < 4; ++j) {
;         const int i0 = 8 * st + 2 * j;
;         f32x2v t = {S[ks][i0], S[ks][i0 + 1]};
;         t = __builtin_elementwise_fma(t, c2v, mcv);
;         f32x2v pv;
;         if (variant == 1) { pv = t; } else {
;         pv.x = __builtin_amdgcn_exp2f(t.x);
;         pv.y = __builtin_amdgcn_exp2f(t.y);
;         }
;         if (MODE != 0) {
;           if (need_mask) {
;             pv.x = (S[ks][i0] > -1e29f) ? pv.x : 0.f;
;             pv.y = (S[ks][i0 + 1] > -1e29f) ? pv.y : 0.f;
;           }
;         }
;         rs2 += pv;
;         pf.u[j] = __builtin_bit_cast(unsigned, __builtin_convertvector(pv, hwbf16x2));
;       }
; #pragma unroll
;       for (int d = 0; d < DV / 32; ++d) {
;         const char* vp = base + C::KBYTES + (d * 32 + lr) * C::VSTR + (ks * 32 + 16 * st + 4 * lh) * 2;
;         const s16x4 lo = *(const s16x4*)vp, hi = *(const s16x4*)(vp + 16);
;         const bf16x8 vf = __builtin_shufflevector(lo, hi, 0, 1, 2, 3, 4, 5, 6, 7);
;         O[d] = MFMA(vf, pf.v, O[d]);
;       }
;     }
;   float rs = rs2.x + rs2.y;
;   rs += __shfl_xor(rs, 32);
;   l += rs;
;     ...
;   asm volatile("s_waitcnt vmcnt(0)" ::: "memory");
; #pragma unroll
;   for (int t = 0; t < NST - 1; ++t)
;     if (t < ntile) FA_ISSUE(t, t)
;   int stage = 0;
;   for (int t = 0; t < ntile; ++t) {
;     int ahead = ((ntile < t + NST - 1) ? ntile : t + NST - 1) - (t + 1);
;     if (NST == 4 && ahead >= 2) wait_vmcnt<2 * NI>();
;     else if (ahead >= 1) wait_vmcnt<NI>();
;     else wait_vmcnt<0>();
;     raw_barrier();
;     if (t + NST - 1 < ntile) {
;       const int sn = (stage == 0) ? NST - 1 : stage - 1;
;       FA_ISSUE(t + NST - 1, sn)
.Lfast_mla1:
	v_mul_f32_e32 v104, 0xbe16c740, v104
	s_mov_b32 s12, 0x3e16c740
	v_pk_fma_f32 v[118:119], v[50:51], s[12:13], v[104:105] op_sel_hi:[1,0,0]
	v_exp_f32_e32 v126, v118
	v_exp_f32_e32 v127, v119
	v_pk_fma_f32 v[50:51], v[52:53], s[12:13], v[104:105] op_sel_hi:[1,0,0]
	v_exp_f32_e32 v128, v50
	v_exp_f32_e32 v129, v51
	v_cvt_pk_bf16_f32 v118, v126, v127
	v_pk_fma_f32 v[50:51], v[54:55], s[12:13], v[104:105] op_sel_hi:[1,0,0]
	v_exp_f32_e32 v130, v50
	v_exp_f32_e32 v131, v51
	v_cvt_pk_bf16_f32 v119, v128, v129
	v_pk_fma_f32 v[50:51], v[56:57], s[12:13], v[104:105] op_sel_hi:[1,0,0]
	v_exp_f32_e32 v56, v50
	v_exp_f32_e32 v57, v51
	v_cvt_pk_bf16_f32 v120, v130, v131
	v_cvt_pk_bf16_f32 v121, v56, v57
	s_waitcnt lgkmcnt(0)
	s_nop 0
	v_mfma_f32_32x32x16_bf16 v[18:33], v[216:219], v[118:121], v[18:33]
	v_mfma_f32_32x32x16_bf16 v[2:17], v[220:223], v[118:121], v[2:17]
	v_add_f32_e64 v52, v126, 0
	v_add_f32_e64 v53, v127, 0
	v_add_f32_e64 v52, v128, v52
	v_add_f32_e64 v53, v129, v53
	v_add_f32_e64 v52, v130, v52
	v_add_f32_e64 v53, v131, v53
	v_pk_add_f32 v[118:119], v[56:57], v[52:53]
	v_pk_fma_f32 v[52:53], v[58:59], s[12:13], v[104:105] op_sel_hi:[1,0,0]
	v_exp_f32_e32 v120, v52
	v_exp_f32_e32 v121, v53
	v_pk_fma_f32 v[54:55], v[60:61], s[12:13], v[104:105] op_sel_hi:[1,0,0]
	v_exp_f32_e32 v60, v54
	v_exp_f32_e32 v61, v55
	v_cvt_pk_bf16_f32 v52, v120, v121
	v_pk_fma_f32 v[54:55], v[62:63], s[12:13], v[104:105] op_sel_hi:[1,0,0]
	v_exp_f32_e32 v62, v54
	v_exp_f32_e32 v63, v55
	v_cvt_pk_bf16_f32 v53, v60, v61
	v_pk_fma_f32 v[56:57], v[64:65], s[12:13], v[104:105] op_sel_hi:[1,0,0]
	v_exp_f32_e32 v64, v56
	v_exp_f32_e32 v65, v57
	v_cvt_pk_bf16_f32 v54, v62, v63
	v_cvt_pk_bf16_f32 v55, v64, v65
	s_nop 1
	v_mfma_f32_32x32x16_bf16 v[18:33], v[224:227], v[52:55], v[18:33]
	v_mfma_f32_32x32x16_bf16 v[2:17], v[228:231], v[52:55], v[2:17]
	v_fma_f32 v54, v34, s12, v104
	v_fma_f32 v55, v35, s12, v104
	v_fma_f32 v56, v36, s12, v104
	v_fma_f32 v57, v37, s12, v104
	v_exp_f32_e32 v54, v54
	v_exp_f32_e32 v55, v55
	v_pk_add_f32 v[52:53], v[120:121], v[118:119]
	v_pk_add_f32 v[52:53], v[60:61], v[52:53]
	v_exp_f32_e32 v56, v56
	v_exp_f32_e32 v57, v57
	v_cvt_pk_bf16_f32 v34, v54, v55
	v_pk_add_f32 v[52:53], v[62:63], v[52:53]
	v_pk_add_f32 v[52:53], v[64:65], v[52:53]
	v_pk_fma_f32 v[36:37], v[38:39], s[12:13], v[104:105] op_sel_hi:[1,0,0]
	v_exp_f32_e32 v58, v36
	v_exp_f32_e32 v59, v37
	v_cvt_pk_bf16_f32 v35, v56, v57
	v_pk_fma_f32 v[38:39], v[40:41], s[12:13], v[104:105] op_sel_hi:[1,0,0]
	v_exp_f32_e32 v60, v38
	v_exp_f32_e32 v61, v39
	v_cvt_pk_bf16_f32 v36, v58, v59
	v_cvt_pk_bf16_f32 v37, v60, v61
	s_nop 1
	v_mfma_f32_32x32x16_bf16 v[18:33], v[232:235], v[34:37], v[18:33]
	v_mfma_f32_32x32x16_bf16 v[2:17], v[236:239], v[34:37], v[2:17]
	v_add_f32_e64 v34, v54, v52
	v_add_f32_e64 v35, v55, v53
	v_add_f32_e64 v34, v56, v34
	v_add_f32_e64 v35, v57, v35
	v_add_f32_e64 v34, v58, v34
	v_add_f32_e64 v35, v59, v35
	v_pk_add_f32 v[52:53], v[60:61], v[34:35]
	v_pk_fma_f32 v[34:35], v[42:43], s[12:13], v[104:105] op_sel_hi:[1,0,0]
	v_exp_f32_e32 v42, v34
	v_exp_f32_e32 v43, v35
	v_pk_fma_f32 v[36:37], v[44:45], s[12:13], v[104:105] op_sel_hi:[1,0,0]
	v_exp_f32_e32 v44, v36
	v_exp_f32_e32 v45, v37
	v_cvt_pk_bf16_f32 v34, v42, v43
	v_pk_fma_f32 v[36:37], v[46:47], s[12:13], v[104:105] op_sel_hi:[1,0,0]
	v_exp_f32_e32 v46, v36
	v_exp_f32_e32 v47, v37
	v_cvt_pk_bf16_f32 v35, v44, v45
	v_pk_fma_f32 v[38:39], v[48:49], s[12:13], v[104:105] op_sel_hi:[1,0,0]
	v_exp_f32_e32 v48, v38
	v_exp_f32_e32 v49, v39
	v_cvt_pk_bf16_f32 v36, v46, v47
	v_cvt_pk_bf16_f32 v37, v48, v49
	s_nop 1
	v_mfma_f32_32x32x16_bf16 v[18:33], v[240:243], v[34:37], v[18:33]
	v_mfma_f32_32x32x16_bf16 v[2:17], v[244:247], v[34:37], v[2:17]
	v_add_f32_e64 v34, v42, v52
	v_add_f32_e64 v35, v43, v53
	v_add_f32_e64 v34, v44, v34
	v_add_f32_e64 v35, v45, v35
	v_add_f32_e64 v34, v46, v34
	v_add_f32_e64 v35, v47, v35
	v_pk_add_f32 v[34:35], v[48:49], v[34:35]
	v_add_f32_e32 v34, v34, v35
	ds_bpermute_b32 v35, v117, v34
	s_cmp_ge_u32 s16, s19
	s_cbranch_scc1 .Ldma_f_mla1
	s_add_i32 s98, s6, 0xffffa800
	s_cmp_lg_u32 s22, 0
	s_cselect_b32 s98, s98, 0x10800
	s_add_i32 s98, s98, 0
	v_add_u32_e32 v247, s98, v107
	s_nop 0
	v_readfirstlane_b32 s99, v247
	v_add_u32_e32 v247, s98, v93
	s_mov_b32 m0, s99
	v_readfirstlane_b32 s99, v247
	v_add_u32_e32 v247, s98, v108
	global_load_lds_dwordx4 v[102:103], off
	s_mov_b32 m0, s99
	v_readfirstlane_b32 s98, v247
	global_load_lds_dwordx4 v[100:101], off
	s_mov_b32 m0, s98
	s_nop 0
	global_load_lds_dwordx4 v[98:99], off

; #define MFMA(a, b, c) __builtin_amdgcn_mfma_f32_32x32x16_bf16((a), (b), (c), 0, 0, 0)
;     ...
;   float mc = m * c2;
;   if (MODE == 2) mc = selbit ? mc : 1e30f;
;   const f32x2v c2v = {c2, c2}, mcv = {-mc, -mc};
;   f32x2v rs2 = {0.f, 0.f};
; #pragma unroll
;   for (int ks = 0; ks < 2; ++ks)
; #pragma unroll
;     for (int st = 0; st < 2; ++st) {
;       union { unsigned u[4]; bf16x8 v; } pf;
; #pragma unroll
;       for (int j = 0; j < 4; ++j) {
;         const int i0 = 8 * st + 2 * j;
;         f32x2v t = {S[ks][i0], S[ks][i0 + 1]};
;         t = __builtin_elementwise_fma(t, c2v, mcv);
;         f32x2v pv;
;         if (variant == 1) { pv = t; } else {
;         pv.x = __builtin_amdgcn_exp2f(t.x);
;         pv.y = __builtin_amdgcn_exp2f(t.y);
;         }
;         if (MODE != 0) {
;           if (need_mask) {
;             pv.x = (S[ks][i0] > -1e29f) ? pv.x : 0.f;
;             pv.y = (S[ks][i0 + 1] > -1e29f) ? pv.y : 0.f;
;           }
;         }
;         rs2 += pv;
;         pf.u[j] = __builtin_bit_cast(unsigned, __builtin_convertvector(pv, hwbf16x2));
;       }
; #pragma unroll
;       for (int d = 0; d < DV / 32; ++d) {
;         const char* vp = base + C::KBYTES + (d * 32 + lr) * C::VSTR + (ks * 32 + 16 * st + 4 * lh) * 2;
;         const s16x4 lo = *(const s16x4*)vp, hi = *(const s16x4*)(vp + 16);
;         const bf16x8 vf = __builtin_shufflevector(lo, hi, 0, 1, 2, 3, 4, 5, 6, 7);
;         O[d] = MFMA(vf, pf.v, O[d]);
.LBB0_424:
	s_cmp_eq_u64 s[8:9], 0
	s_cbranch_scc1 .Lfast_sel1
	v_mul_f32_e32 v110, 0xbe38aa3b, v110
	v_cndmask_b32_e64 v110, v208, v110, s[10:11]
	v_pk_fma_f32 v[120:121], v[82:83], s[96:97], v[110:111] op_sel_hi:[1,0,0]
	v_cmp_lt_f32_e32 vcc, s33, v82
	v_exp_f32_e32 v119, v120
	v_exp_f32_e32 v120, v121
	v_cndmask_b32_e32 v82, 0, v119, vcc
	v_cmp_lt_f32_e32 vcc, s33, v83
	v_cndmask_b32_e64 v128, v119, v82, s[8:9]
	s_nop 0
	v_cndmask_b32_e32 v83, 0, v120, vcc
	v_cndmask_b32_e64 v129, v120, v83, s[8:9]
	v_pk_fma_f32 v[82:83], v[84:85], s[96:97], v[110:111] op_sel_hi:[1,0,0]
	v_cmp_lt_f32_e32 vcc, s33, v84
	v_exp_f32_e32 v82, v82
	v_exp_f32_e32 v83, v83
	v_cvt_pk_bf16_f32 v120, v128, v129
	v_cndmask_b32_e32 v84, 0, v82, vcc
	v_cmp_lt_f32_e32 vcc, s33, v85
	v_cndmask_b32_e64 v152, v82, v84, s[8:9]
	s_nop 0
	v_cndmask_b32_e32 v85, 0, v83, vcc
	v_cndmask_b32_e64 v153, v83, v85, s[8:9]
	v_pk_fma_f32 v[82:83], v[86:87], s[96:97], v[110:111] op_sel_hi:[1,0,0]
	v_cmp_lt_f32_e32 vcc, s33, v86
	v_exp_f32_e32 v82, v82
	v_exp_f32_e32 v83, v83
	v_cvt_pk_bf16_f32 v121, v152, v153
	v_cndmask_b32_e32 v84, 0, v82, vcc
	v_cmp_lt_f32_e32 vcc, s33, v87
	v_cndmask_b32_e64 v154, v82, v84, s[8:9]
	s_nop 0
	v_cndmask_b32_e32 v85, 0, v83, vcc
	v_cndmask_b32_e64 v155, v83, v85, s[8:9]
	v_pk_fma_f32 v[82:83], v[88:89], s[96:97], v[110:111] op_sel_hi:[1,0,0]
	v_cmp_lt_f32_e32 vcc, s33, v88
	v_exp_f32_e32 v82, v82
	v_exp_f32_e32 v83, v83
	v_cvt_pk_bf16_f32 v122, v154, v155
	v_cndmask_b32_e32 v84, 0, v82, vcc
	v_cmp_lt_f32_e32 vcc, s33, v89
	v_cndmask_b32_e64 v88, v82, v84, s[8:9]
	s_nop 0
	v_cndmask_b32_e32 v85, 0, v83, vcc
	v_cndmask_b32_e64 v89, v83, v85, s[8:9]
	s_nop 0
	s_nop 0
	s_nop 0
	s_nop 0
	v_cvt_pk_bf16_f32 v123, v88, v89
	s_nop 0
	v_cmp_lt_f32_e32 vcc, s33, v90
	s_waitcnt lgkmcnt(0)
	v_mfma_f32_32x32x16_bf16 v[50:65], v[216:219], v[120:123], v[50:65]
	s_nop 0
	s_waitcnt lgkmcnt(0)
	v_mfma_f32_32x32x16_bf16 v[34:49], v[220:223], v[120:123], v[34:49]
	v_add_f32_e64 v84, v128, 0
	v_add_f32_e64 v85, v129, 0
	v_add_f32_e64 v84, v152, v84
	v_add_f32_e64 v85, v153, v85
	v_add_f32_e64 v84, v154, v84
	v_add_f32_e64 v85, v155, v85
	v_pk_add_f32 v[120:121], v[88:89], v[84:85]
	v_pk_fma_f32 v[84:85], v[90:91], s[96:97], v[110:111] op_sel_hi:[1,0,0]
	s_nop 0
	v_exp_f32_e32 v84, v84
	v_exp_f32_e32 v85, v85
	v_cndmask_b32_e32 v86, 0, v84, vcc
	v_cmp_lt_f32_e32 vcc, s33, v91
	v_cndmask_b32_e64 v122, v84, v86, s[8:9]
	s_nop 0
	v_cndmask_b32_e32 v87, 0, v85, vcc
	v_cndmask_b32_e64 v123, v85, v87, s[8:9]
	v_pk_fma_f32 v[86:87], v[92:93], s[96:97], v[110:111] op_sel_hi:[1,0,0]
	v_cmp_lt_f32_e32 vcc, s33, v92
	v_exp_f32_e32 v85, v86
	v_exp_f32_e32 v86, v87
	v_cvt_pk_bf16_f32 v84, v122, v123
	v_cndmask_b32_e32 v87, 0, v85, vcc
	v_cmp_lt_f32_e32 vcc, s33, v93
	v_cndmask_b32_e64 v92, v85, v87, s[8:9]
	s_nop 0
	v_cndmask_b32_e32 v88, 0, v86, vcc
	v_cndmask_b32_e64 v93, v86, v88, s[8:9]
	v_pk_fma_f32 v[86:87], v[94:95], s[96:97], v[110:111] op_sel_hi:[1,0,0]
	v_cmp_lt_f32_e32 vcc, s33, v94
	v_exp_f32_e32 v86, v86
	v_exp_f32_e32 v87, v87
	v_cvt_pk_bf16_f32 v85, v92, v93
	v_cndmask_b32_e32 v88, 0, v86, vcc
	v_cmp_lt_f32_e32 vcc, s33, v95
	v_cndmask_b32_e64 v94, v86, v88, s[8:9]
	s_nop 0
	v_cndmask_b32_e32 v89, 0, v87, vcc
	v_cndmask_b32_e64 v95, v87, v89, s[8:9]
	v_pk_fma_f32 v[88:89], v[96:97], s[96:97], v[110:111] op_sel_hi:[1,0,0]
	v_cmp_lt_f32_e32 vcc, s33, v96
	v_exp_f32_e32 v87, v88
	v_exp_f32_e32 v88, v89
	v_cvt_pk_bf16_f32 v86, v94, v95
	v_cndmask_b32_e32 v89, 0, v87, vcc
	v_cmp_lt_f32_e32 vcc, s33, v97
	v_cndmask_b32_e64 v96, v87, v89, s[8:9]
	s_nop 0
	v_cndmask_b32_e32 v90, 0, v88, vcc
	v_cndmask_b32_e64 v97, v88, v90, s[8:9]
	s_nop 0
	v_cvt_pk_bf16_f32 v87, v96, v97
	v_cmp_lt_f32_e32 vcc, s33, v66
	s_nop 0
	v_mfma_f32_32x32x16_bf16 v[50:65], v[224:227], v[84:87], v[50:65]
	v_mfma_f32_32x32x16_bf16 v[34:49], v[228:231], v[84:87], v[34:49]
	v_fma_f32 v86, v66, s96, v110
	v_fma_f32 v87, v67, s96, v110
	v_fma_f32 v88, v68, s96, v110
	v_fma_f32 v89, v69, s96, v110
	v_exp_f32_e32 v86, v86
	v_exp_f32_e32 v87, v87
	v_pk_add_f32 v[84:85], v[122:123], v[120:121]
	v_cndmask_b32_e32 v66, 0, v86, vcc
	v_cmp_lt_f32_e32 vcc, s33, v67
	v_pk_add_f32 v[84:85], v[92:93], v[84:85]
	v_cndmask_b32_e64 v86, v86, v66, s[8:9]
	v_cndmask_b32_e32 v67, 0, v87, vcc
	v_cndmask_b32_e64 v87, v87, v67, s[8:9]
	v_exp_f32_e32 v67, v88
	v_exp_f32_e32 v88, v89
	v_cmp_lt_f32_e32 vcc, s33, v68
	v_cvt_pk_bf16_f32 v66, v86, v87
	v_pk_add_f32 v[84:85], v[94:95], v[84:85]
	v_cndmask_b32_e32 v68, 0, v67, vcc
	v_cmp_lt_f32_e32 vcc, s33, v69
	v_pk_add_f32 v[84:85], v[96:97], v[84:85]
	s_nop 0
	v_cndmask_b32_e32 v69, 0, v88, vcc
	v_cndmask_b32_e64 v89, v88, v69, s[8:9]
	v_cndmask_b32_e64 v88, v67, v68, s[8:9]
	v_pk_fma_f32 v[68:69], v[70:71], s[96:97], v[110:111] op_sel_hi:[1,0,0]
	v_cmp_lt_f32_e32 vcc, s33, v70
	v_exp_f32_e32 v68, v68
	v_exp_f32_e32 v69, v69
	v_cvt_pk_bf16_f32 v67, v88, v89
	v_cndmask_b32_e32 v70, 0, v68, vcc
	v_cmp_lt_f32_e32 vcc, s33, v71
	v_cndmask_b32_e64 v90, v68, v70, s[8:9]
	s_nop 0
	v_cndmask_b32_e32 v71, 0, v69, vcc
	v_cndmask_b32_e64 v91, v69, v71, s[8:9]
	v_pk_fma_f32 v[70:71], v[72:73], s[96:97], v[110:111] op_sel_hi:[1,0,0]
	v_cmp_lt_f32_e32 vcc, s33, v72
	v_exp_f32_e32 v69, v70
	v_exp_f32_e32 v70, v71
	v_cvt_pk_bf16_f32 v68, v90, v91
	v_cndmask_b32_e32 v71, 0, v69, vcc
	v_cmp_lt_f32_e32 vcc, s33, v73
	v_cndmask_b32_e64 v92, v69, v71, s[8:9]
	s_nop 0
	v_cndmask_b32_e32 v72, 0, v70, vcc
	v_cndmask_b32_e64 v93, v70, v72, s[8:9]
	s_nop 0
	v_cvt_pk_bf16_f32 v69, v92, v93
	v_cmp_lt_f32_e32 vcc, s33, v74
	s_waitcnt lgkmcnt(0)
; #define MFMA(a, b, c) __builtin_amdgcn_mfma_f32_32x32x16_bf16((a), (b), (c), 0, 0, 0)
; template <int N> DI void wait_vmcnt() { asm volatile("s_waitcnt vmcnt(%0)" ::"n"(N) : "memory"); }
;     ...
; #pragma unroll
;   for (int ks = 0; ks < 2; ++ks)
; #pragma unroll
;     for (int st = 0; st < 2; ++st) {
;       union { unsigned u[4]; bf16x8 v; } pf;
; #pragma unroll
;       for (int j = 0; j < 4; ++j) {
;         const int i0 = 8 * st + 2 * j;
;         f32x2v t = {S[ks][i0], S[ks][i0 + 1]};
;         t = __builtin_elementwise_fma(t, c2v, mcv);
;         f32x2v pv;
;         if (variant == 1) { pv = t; } else {
;         pv.x = __builtin_amdgcn_exp2f(t.x);
;         pv.y = __builtin_amdgcn_exp2f(t.y);
;         }
;         if (MODE != 0) {
;           if (need_mask) {
;             pv.x = (S[ks][i0] > -1e29f) ? pv.x : 0.f;
;             pv.y = (S[ks][i0 + 1] > -1e29f) ? pv.y : 0.f;
;           }
;         }
;         rs2 += pv;
;         pf.u[j] = __builtin_bit_cast(unsigned, __builtin_convertvector(pv, hwbf16x2));
;       }
; #pragma unroll
;       for (int d = 0; d < DV / 32; ++d) {
;         const char* vp = base + C::KBYTES + (d * 32 + lr) * C::VSTR + (ks * 32 + 16 * st + 4 * lh) * 2;
;         const s16x4 lo = *(const s16x4*)vp, hi = *(const s16x4*)(vp + 16);
;         const bf16x8 vf = __builtin_shufflevector(lo, hi, 0, 1, 2, 3, 4, 5, 6, 7);
;         O[d] = MFMA(vf, pf.v, O[d]);
;       }
;     }
;   float rs = rs2.x + rs2.y;
;   rs += __shfl_xor(rs, 32);
;   l += rs;
;     ...
;   asm volatile("s_waitcnt vmcnt(0)" ::: "memory");
; #pragma unroll
;   for (int t = 0; t < NST - 1; ++t)
;     if (t < ntile) FA_ISSUE(t, t)
;   int stage = 0;
;   for (int t = 0; t < ntile; ++t) {
;     int ahead = ((ntile < t + NST - 1) ? ntile : t + NST - 1) - (t + 1);
;     if (NST == 4 && ahead >= 2) wait_vmcnt<2 * NI>();
;     else if (ahead >= 1) wait_vmcnt<NI>();
;     else wait_vmcnt<0>();
;     raw_barrier();
;     if (t + NST - 1 < ntile) {
;       const int sn = (stage == 0) ? NST - 1 : stage - 1;
;       FA_ISSUE(t + NST - 1, sn)
	v_mfma_f32_32x32x16_bf16 v[50:65], v[232:235], v[66:69], v[50:65]
	s_nop 0
	s_waitcnt lgkmcnt(0)
	v_mfma_f32_32x32x16_bf16 v[34:49], v[236:239], v[66:69], v[34:49]
	v_add_f32_e64 v66, v86, v84
	v_add_f32_e64 v67, v87, v85
	v_add_f32_e64 v66, v88, v66
	v_add_f32_e64 v67, v89, v67
	v_add_f32_e64 v66, v90, v66
	v_add_f32_e64 v67, v91, v67
	v_pk_add_f32 v[84:85], v[92:93], v[66:67]
	v_pk_fma_f32 v[66:67], v[74:75], s[96:97], v[110:111] op_sel_hi:[1,0,0]
	s_nop 0
	v_exp_f32_e32 v66, v66
	v_exp_f32_e32 v67, v67
	v_cndmask_b32_e32 v68, 0, v66, vcc
	v_cmp_lt_f32_e32 vcc, s33, v75
	v_cndmask_b32_e64 v74, v66, v68, s[8:9]
	s_nop 0
	v_cndmask_b32_e32 v69, 0, v67, vcc
	v_cndmask_b32_e64 v75, v67, v69, s[8:9]
	v_pk_fma_f32 v[68:69], v[76:77], s[96:97], v[110:111] op_sel_hi:[1,0,0]
	v_cmp_lt_f32_e32 vcc, s33, v76
	v_exp_f32_e32 v67, v68
	v_exp_f32_e32 v68, v69
	v_cvt_pk_bf16_f32 v66, v74, v75
	v_cndmask_b32_e32 v69, 0, v67, vcc
	v_cmp_lt_f32_e32 vcc, s33, v77
	v_cndmask_b32_e64 v76, v67, v69, s[8:9]
	s_nop 0
	v_cndmask_b32_e32 v70, 0, v68, vcc
	v_cndmask_b32_e64 v77, v68, v70, s[8:9]
	v_pk_fma_f32 v[68:69], v[78:79], s[96:97], v[110:111] op_sel_hi:[1,0,0]
	v_cmp_lt_f32_e32 vcc, s33, v78
	v_exp_f32_e32 v68, v68
	v_exp_f32_e32 v69, v69
	v_cvt_pk_bf16_f32 v67, v76, v77
	v_cndmask_b32_e32 v70, 0, v68, vcc
	v_cmp_lt_f32_e32 vcc, s33, v79
	v_cndmask_b32_e64 v78, v68, v70, s[8:9]
	s_nop 0
	v_cndmask_b32_e32 v71, 0, v69, vcc
	v_cndmask_b32_e64 v79, v69, v71, s[8:9]
	v_pk_fma_f32 v[70:71], v[80:81], s[96:97], v[110:111] op_sel_hi:[1,0,0]
	v_cmp_lt_f32_e32 vcc, s33, v80
	v_exp_f32_e32 v69, v70
	v_exp_f32_e32 v70, v71
	v_cvt_pk_bf16_f32 v68, v78, v79
	v_cndmask_b32_e32 v71, 0, v69, vcc
	v_cmp_lt_f32_e32 vcc, s33, v81
	v_cndmask_b32_e64 v80, v69, v71, s[8:9]
	s_nop 0
	v_cndmask_b32_e32 v72, 0, v70, vcc
	v_cndmask_b32_e64 v81, v70, v72, s[8:9]
	s_nop 0
	v_cvt_pk_bf16_f32 v69, v80, v81
	s_nop 1
	v_mfma_f32_32x32x16_bf16 v[50:65], v[240:243], v[66:69], v[50:65]
	s_nop 0
	s_waitcnt lgkmcnt(0)
	v_mfma_f32_32x32x16_bf16 v[34:49], v[244:247], v[66:69], v[34:49]
	v_add_f32_e64 v66, v74, v84
	v_add_f32_e64 v67, v75, v85
	v_add_f32_e64 v66, v76, v66
	v_add_f32_e64 v67, v77, v67
	v_add_f32_e64 v66, v78, v66
	v_add_f32_e64 v67, v79, v67
	v_pk_add_f32 v[66:67], v[80:81], v[66:67]
	s_nop 0
	v_add_f32_e32 v66, v66, v67
	ds_bpermute_b32 v67, v165, v66
	s_add_i32 s98, s0, 3
	s_cmp_gt_u32 s98, s46
	s_cbranch_scc1 .Ldma_m_sel1
	s_add_i32 s98, s6, 0xffffb800
	s_cmp_lg_u32 s48, 0
	s_cselect_b32 s98, s98, 0xd800
	s_add_i32 s98, s98, 0
	v_add_u32_e32 v247, s98, v112
	s_nop 0
	v_readfirstlane_b32 s99, v247
	v_add_u32_e32 v247, s98, v111
	s_mov_b32 m0, s99
	v_readfirstlane_b32 s99, v247
	v_add_u32_e32 v247, s98, v113
	global_load_lds_dwordx4 v[108:109], off
	s_mov_b32 m0, s99
	v_readfirstlane_b32 s98, v247
	global_load_lds_dwordx4 v[106:107], off
	s_mov_b32 m0, s98
	s_nop 0
	global_load_lds_dwordx4 v[104:105], off

; #define MFMA(a, b, c) __builtin_amdgcn_mfma_f32_32x32x16_bf16((a), (b), (c), 0, 0, 0)
; template <int N> DI void wait_vmcnt() { asm volatile("s_waitcnt vmcnt(%0)" ::"n"(N) : "memory"); }
;     ...
;   float mc = m * c2;
;   if (MODE == 2) mc = selbit ? mc : 1e30f;
;   const f32x2v c2v = {c2, c2}, mcv = {-mc, -mc};
;   f32x2v rs2 = {0.f, 0.f};
; #pragma unroll
;   for (int ks = 0; ks < 2; ++ks)
; #pragma unroll
;     for (int st = 0; st < 2; ++st) {
;       union { unsigned u[4]; bf16x8 v; } pf;
; #pragma unroll
;       for (int j = 0; j < 4; ++j) {
;         const int i0 = 8 * st + 2 * j;
;         f32x2v t = {S[ks][i0], S[ks][i0 + 1]};
;         t = __builtin_elementwise_fma(t, c2v, mcv);
;         f32x2v pv;
;         if (variant == 1) { pv = t; } else {
;         pv.x = __builtin_amdgcn_exp2f(t.x);
;         pv.y = __builtin_amdgcn_exp2f(t.y);
;         }
;         if (MODE != 0) {
;           if (need_mask) {
;             pv.x = (S[ks][i0] > -1e29f) ? pv.x : 0.f;
;             pv.y = (S[ks][i0 + 1] > -1e29f) ? pv.y : 0.f;
;           }
;         }
;         rs2 += pv;
;         pf.u[j] = __builtin_bit_cast(unsigned, __builtin_convertvector(pv, hwbf16x2));
;       }
; #pragma unroll
;       for (int d = 0; d < DV / 32; ++d) {
;         const char* vp = base + C::KBYTES + (d * 32 + lr) * C::VSTR + (ks * 32 + 16 * st + 4 * lh) * 2;
;         const s16x4 lo = *(const s16x4*)vp, hi = *(const s16x4*)(vp + 16);
;         const bf16x8 vf = __builtin_shufflevector(lo, hi, 0, 1, 2, 3, 4, 5, 6, 7);
;         O[d] = MFMA(vf, pf.v, O[d]);
;       }
;     }
;   float rs = rs2.x + rs2.y;
;   rs += __shfl_xor(rs, 32);
;   l += rs;
;     ...
;   asm volatile("s_waitcnt vmcnt(0)" ::: "memory");
; #pragma unroll
;   for (int t = 0; t < NST - 1; ++t)
;     if (t < ntile) FA_ISSUE(t, t)
;   int stage = 0;
;   for (int t = 0; t < ntile; ++t) {
;     int ahead = ((ntile < t + NST - 1) ? ntile : t + NST - 1) - (t + 1);
;     if (NST == 4 && ahead >= 2) wait_vmcnt<2 * NI>();
;     else if (ahead >= 1) wait_vmcnt<NI>();
;     else wait_vmcnt<0>();
;     raw_barrier();
;     if (t + NST - 1 < ntile) {
;       const int sn = (stage == 0) ? NST - 1 : stage - 1;
;       FA_ISSUE(t + NST - 1, sn)
.Lfast_sel1:
	v_mul_f32_e32 v110, 0xbe38aa3b, v110
	v_cndmask_b32_e64 v110, v208, v110, s[10:11]
	v_pk_fma_f32 v[120:121], v[82:83], s[96:97], v[110:111] op_sel_hi:[1,0,0]
	v_exp_f32_e32 v128, v120
	v_exp_f32_e32 v129, v121
	v_pk_fma_f32 v[82:83], v[84:85], s[96:97], v[110:111] op_sel_hi:[1,0,0]
	v_exp_f32_e32 v152, v82
	v_exp_f32_e32 v153, v83
	v_cvt_pk_bf16_f32 v120, v128, v129
	v_pk_fma_f32 v[82:83], v[86:87], s[96:97], v[110:111] op_sel_hi:[1,0,0]
	v_exp_f32_e32 v154, v82
	v_exp_f32_e32 v155, v83
	v_cvt_pk_bf16_f32 v121, v152, v153
	v_pk_fma_f32 v[82:83], v[88:89], s[96:97], v[110:111] op_sel_hi:[1,0,0]
	v_exp_f32_e32 v88, v82
	v_exp_f32_e32 v89, v83
	v_cvt_pk_bf16_f32 v122, v154, v155
	v_cvt_pk_bf16_f32 v123, v88, v89
	s_waitcnt lgkmcnt(0)
	s_nop 0
	v_mfma_f32_32x32x16_bf16 v[50:65], v[216:219], v[120:123], v[50:65]
	v_mfma_f32_32x32x16_bf16 v[34:49], v[220:223], v[120:123], v[34:49]
	v_add_f32_e64 v84, v128, 0
	v_add_f32_e64 v85, v129, 0
	v_add_f32_e64 v84, v152, v84
	v_add_f32_e64 v85, v153, v85
	v_add_f32_e64 v84, v154, v84
	v_add_f32_e64 v85, v155, v85
	v_pk_add_f32 v[120:121], v[88:89], v[84:85]
	v_pk_fma_f32 v[84:85], v[90:91], s[96:97], v[110:111] op_sel_hi:[1,0,0]
	v_exp_f32_e32 v122, v84
	v_exp_f32_e32 v123, v85
	v_pk_fma_f32 v[86:87], v[92:93], s[96:97], v[110:111] op_sel_hi:[1,0,0]
	v_exp_f32_e32 v92, v86
	v_exp_f32_e32 v93, v87
	v_cvt_pk_bf16_f32 v84, v122, v123
	v_pk_fma_f32 v[86:87], v[94:95], s[96:97], v[110:111] op_sel_hi:[1,0,0]
	v_exp_f32_e32 v94, v86
	v_exp_f32_e32 v95, v87
	v_cvt_pk_bf16_f32 v85, v92, v93
	v_pk_fma_f32 v[88:89], v[96:97], s[96:97], v[110:111] op_sel_hi:[1,0,0]
	v_exp_f32_e32 v96, v88
	v_exp_f32_e32 v97, v89
	v_cvt_pk_bf16_f32 v86, v94, v95
	v_cvt_pk_bf16_f32 v87, v96, v97
	s_nop 1
	v_mfma_f32_32x32x16_bf16 v[50:65], v[224:227], v[84:87], v[50:65]
	v_mfma_f32_32x32x16_bf16 v[34:49], v[228:231], v[84:87], v[34:49]
	v_fma_f32 v86, v66, s96, v110
	v_fma_f32 v87, v67, s96, v110
	v_fma_f32 v88, v68, s96, v110
	v_fma_f32 v89, v69, s96, v110
	v_exp_f32_e32 v86, v86
	v_exp_f32_e32 v87, v87
	v_pk_add_f32 v[84:85], v[122:123], v[120:121]
	v_pk_add_f32 v[84:85], v[92:93], v[84:85]
	v_exp_f32_e32 v88, v88
	v_exp_f32_e32 v89, v89
	v_cvt_pk_bf16_f32 v66, v86, v87
	v_pk_add_f32 v[84:85], v[94:95], v[84:85]
	v_pk_add_f32 v[84:85], v[96:97], v[84:85]
	v_pk_fma_f32 v[68:69], v[70:71], s[96:97], v[110:111] op_sel_hi:[1,0,0]
	v_exp_f32_e32 v90, v68
	v_exp_f32_e32 v91, v69
	v_cvt_pk_bf16_f32 v67, v88, v89
	v_pk_fma_f32 v[70:71], v[72:73], s[96:97], v[110:111] op_sel_hi:[1,0,0]
	v_exp_f32_e32 v92, v70
	v_exp_f32_e32 v93, v71
	v_cvt_pk_bf16_f32 v68, v90, v91
	v_cvt_pk_bf16_f32 v69, v92, v93
	s_nop 1
	v_mfma_f32_32x32x16_bf16 v[50:65], v[232:235], v[66:69], v[50:65]
	v_mfma_f32_32x32x16_bf16 v[34:49], v[236:239], v[66:69], v[34:49]
	v_add_f32_e64 v66, v86, v84
	v_add_f32_e64 v67, v87, v85
	v_add_f32_e64 v66, v88, v66
	v_add_f32_e64 v67, v89, v67
	v_add_f32_e64 v66, v90, v66
	v_add_f32_e64 v67, v91, v67
	v_pk_add_f32 v[84:85], v[92:93], v[66:67]
	v_pk_fma_f32 v[66:67], v[74:75], s[96:97], v[110:111] op_sel_hi:[1,0,0]
	v_exp_f32_e32 v74, v66
	v_exp_f32_e32 v75, v67
	v_pk_fma_f32 v[68:69], v[76:77], s[96:97], v[110:111] op_sel_hi:[1,0,0]
	v_exp_f32_e32 v76, v68
	v_exp_f32_e32 v77, v69
	v_cvt_pk_bf16_f32 v66, v74, v75
	v_pk_fma_f32 v[68:69], v[78:79], s[96:97], v[110:111] op_sel_hi:[1,0,0]
	v_exp_f32_e32 v78, v68
	v_exp_f32_e32 v79, v69
	v_cvt_pk_bf16_f32 v67, v76, v77
	v_pk_fma_f32 v[70:71], v[80:81], s[96:97], v[110:111] op_sel_hi:[1,0,0]
	v_exp_f32_e32 v80, v70
	v_exp_f32_e32 v81, v71
	v_cvt_pk_bf16_f32 v68, v78, v79
	v_cvt_pk_bf16_f32 v69, v80, v81
	s_nop 1
	v_mfma_f32_32x32x16_bf16 v[50:65], v[240:243], v[66:69], v[50:65]
	v_mfma_f32_32x32x16_bf16 v[34:49], v[244:247], v[66:69], v[34:49]
	v_add_f32_e64 v66, v74, v84
	v_add_f32_e64 v67, v75, v85
	v_add_f32_e64 v66, v76, v66
	v_add_f32_e64 v67, v77, v67
	v_add_f32_e64 v66, v78, v66
	v_add_f32_e64 v67, v79, v67
	v_pk_add_f32 v[66:67], v[80:81], v[66:67]
	v_add_f32_e32 v66, v66, v67
	ds_bpermute_b32 v67, v165, v66
	s_add_i32 s98, s0, 3
	s_cmp_gt_u32 s98, s46
	s_cbranch_scc1 .Ldma_f_sel1
	s_add_i32 s98, s6, 0xffffb800
	s_cmp_lg_u32 s48, 0
	s_cselect_b32 s98, s98, 0xd800
	s_add_i32 s98, s98, 0
	v_add_u32_e32 v247, s98, v112
	s_nop 0
	v_readfirstlane_b32 s99, v247
	v_add_u32_e32 v247, s98, v111
	s_mov_b32 m0, s99
	v_readfirstlane_b32 s99, v247
	v_add_u32_e32 v247, s98, v113
	global_load_lds_dwordx4 v[108:109], off
	s_mov_b32 m0, s99
	v_readfirstlane_b32 s98, v247
	global_load_lds_dwordx4 v[106:107], off
	s_mov_b32 m0, s98
	s_nop 0
	global_load_lds_dwordx4 v[104:105], off

; #define MFMA(a, b, c) __builtin_amdgcn_mfma_f32_32x32x16_bf16((a), (b), (c), 0, 0, 0)
;     ...
;   float mc = m * c2;
;   if (MODE == 2) mc = selbit ? mc : 1e30f;
;   const f32x2v c2v = {c2, c2}, mcv = {-mc, -mc};
;   f32x2v rs2 = {0.f, 0.f};
; #pragma unroll
;   for (int ks = 0; ks < 2; ++ks)
; #pragma unroll
;     for (int st = 0; st < 2; ++st) {
;       union { unsigned u[4]; bf16x8 v; } pf;
; #pragma unroll
;       for (int j = 0; j < 4; ++j) {
;         const int i0 = 8 * st + 2 * j;
;         f32x2v t = {S[ks][i0], S[ks][i0 + 1]};
;         t = __builtin_elementwise_fma(t, c2v, mcv);
;         f32x2v pv;
;         if (variant == 1) { pv = t; } else {
;         pv.x = __builtin_amdgcn_exp2f(t.x);
;         pv.y = __builtin_amdgcn_exp2f(t.y);
;         }
;         if (MODE != 0) {
;           if (need_mask) {
;             pv.x = (S[ks][i0] > -1e29f) ? pv.x : 0.f;
;             pv.y = (S[ks][i0 + 1] > -1e29f) ? pv.y : 0.f;
;           }
;         }
;         rs2 += pv;
;         pf.u[j] = __builtin_bit_cast(unsigned, __builtin_convertvector(pv, hwbf16x2));
;       }
; #pragma unroll
;       for (int d = 0; d < DV / 32; ++d) {
;         const char* vp = base + C::KBYTES + (d * 32 + lr) * C::VSTR + (ks * 32 + 16 * st + 4 * lh) * 2;
;         const s16x4 lo = *(const s16x4*)vp, hi = *(const s16x4*)(vp + 16);
;         const bf16x8 vf = __builtin_shufflevector(lo, hi, 0, 1, 2, 3, 4, 5, 6, 7);
;         O[d] = MFMA(vf, pf.v, O[d]);
;       }
;     }
.LBB0_455:
	s_cmp_eq_u64 s[8:9], 0
	s_cbranch_scc1 .Lfast_win1
	v_mul_f32_e32 v162, 0xbe38aa3b, v162
	v_pk_fma_f32 v[180:181], v[114:115], s[96:97], v[162:163] op_sel_hi:[1,0,0]
	v_cmp_lt_f32_e32 vcc, s33, v114
	v_exp_f32_e32 v179, v180
	v_exp_f32_e32 v180, v181
	v_cndmask_b32_e32 v114, 0, v179, vcc
	v_cmp_lt_f32_e32 vcc, s33, v115
	v_cndmask_b32_e64 v188, v179, v114, s[8:9]
	s_nop 0
	v_cndmask_b32_e32 v115, 0, v180, vcc
	v_cndmask_b32_e64 v189, v180, v115, s[8:9]
	v_pk_fma_f32 v[114:115], v[116:117], s[96:97], v[162:163] op_sel_hi:[1,0,0]
	v_cmp_lt_f32_e32 vcc, s33, v116
	v_exp_f32_e32 v114, v114
	v_exp_f32_e32 v115, v115
	v_cvt_pk_bf16_f32 v180, v188, v189
	v_cndmask_b32_e32 v116, 0, v114, vcc
	v_cmp_lt_f32_e32 vcc, s33, v117
	v_cndmask_b32_e64 v190, v114, v116, s[8:9]
	s_nop 0
	v_cndmask_b32_e32 v117, 0, v115, vcc
	v_cndmask_b32_e64 v191, v115, v117, s[8:9]
	v_pk_fma_f32 v[114:115], v[118:119], s[96:97], v[162:163] op_sel_hi:[1,0,0]
	v_cmp_lt_f32_e32 vcc, s33, v118
	v_exp_f32_e32 v114, v114
	v_exp_f32_e32 v115, v115
	v_cvt_pk_bf16_f32 v181, v190, v191
	v_cndmask_b32_e32 v116, 0, v114, vcc
	v_cmp_lt_f32_e32 vcc, s33, v119
	v_cndmask_b32_e64 v192, v114, v116, s[8:9]
	s_nop 0
	v_cndmask_b32_e32 v117, 0, v115, vcc
	v_cndmask_b32_e64 v193, v115, v117, s[8:9]
	v_pk_fma_f32 v[114:115], v[120:121], s[96:97], v[162:163] op_sel_hi:[1,0,0]
	v_cmp_lt_f32_e32 vcc, s33, v120
	v_exp_f32_e32 v114, v114
	v_exp_f32_e32 v115, v115
	v_cvt_pk_bf16_f32 v182, v192, v193
	v_cndmask_b32_e32 v116, 0, v114, vcc
	v_cmp_lt_f32_e32 vcc, s33, v121
	v_cndmask_b32_e64 v120, v114, v116, s[8:9]
	s_nop 0
	v_cndmask_b32_e32 v117, 0, v115, vcc
	v_cndmask_b32_e64 v121, v115, v117, s[8:9]
	s_nop 0
	s_nop 0
	s_nop 0
	s_nop 0
	v_cvt_pk_bf16_f32 v183, v120, v121
	s_nop 0
	v_cmp_lt_f32_e32 vcc, s33, v122
	s_waitcnt lgkmcnt(0)
	v_mfma_f32_32x32x16_bf16 v[82:97], v[216:219], v[180:183], v[82:97]
	s_nop 0
	s_waitcnt lgkmcnt(0)
	v_mfma_f32_32x32x16_bf16 v[66:81], v[220:223], v[180:183], v[66:81]
	v_add_f32_e64 v116, v188, 0
	v_add_f32_e64 v117, v189, 0
	v_add_f32_e64 v116, v190, v116
	v_add_f32_e64 v117, v191, v117
	v_add_f32_e64 v116, v192, v116
	v_add_f32_e64 v117, v193, v117
	v_pk_add_f32 v[180:181], v[120:121], v[116:117]
	v_pk_fma_f32 v[116:117], v[122:123], s[96:97], v[162:163] op_sel_hi:[1,0,0]
	s_nop 0
	v_exp_f32_e32 v116, v116
	v_exp_f32_e32 v117, v117
	v_cndmask_b32_e32 v118, 0, v116, vcc
	v_cmp_lt_f32_e32 vcc, s33, v123
	v_cndmask_b32_e64 v182, v116, v118, s[8:9]
	s_nop 0
	v_cndmask_b32_e32 v119, 0, v117, vcc
	v_cndmask_b32_e64 v183, v117, v119, s[8:9]
	v_pk_fma_f32 v[118:119], v[124:125], s[96:97], v[162:163] op_sel_hi:[1,0,0]
	v_cmp_lt_f32_e32 vcc, s33, v124
	v_exp_f32_e32 v117, v118
	v_exp_f32_e32 v118, v119
	v_cvt_pk_bf16_f32 v116, v182, v183
	v_cndmask_b32_e32 v119, 0, v117, vcc
	v_cmp_lt_f32_e32 vcc, s33, v125
	v_cndmask_b32_e64 v124, v117, v119, s[8:9]
	s_nop 0
	v_cndmask_b32_e32 v120, 0, v118, vcc
	v_cndmask_b32_e64 v125, v118, v120, s[8:9]
	v_pk_fma_f32 v[118:119], v[126:127], s[96:97], v[162:163] op_sel_hi:[1,0,0]
	v_cmp_lt_f32_e32 vcc, s33, v126
	v_exp_f32_e32 v118, v118
	v_exp_f32_e32 v119, v119
	v_cvt_pk_bf16_f32 v117, v124, v125
	v_cndmask_b32_e32 v120, 0, v118, vcc
	v_cmp_lt_f32_e32 vcc, s33, v127
	v_cndmask_b32_e64 v126, v118, v120, s[8:9]
	s_nop 0
	v_cndmask_b32_e32 v121, 0, v119, vcc
	v_cndmask_b32_e64 v127, v119, v121, s[8:9]
	v_pk_fma_f32 v[120:121], v[128:129], s[96:97], v[162:163] op_sel_hi:[1,0,0]
	v_cmp_lt_f32_e32 vcc, s33, v128
	v_exp_f32_e32 v119, v120
	v_exp_f32_e32 v120, v121
	v_cvt_pk_bf16_f32 v118, v126, v127
	v_cndmask_b32_e32 v121, 0, v119, vcc
	v_cmp_lt_f32_e32 vcc, s33, v129
	v_cndmask_b32_e64 v128, v119, v121, s[8:9]
	s_nop 0
	v_cndmask_b32_e32 v122, 0, v120, vcc
	v_cndmask_b32_e64 v129, v120, v122, s[8:9]
	s_nop 0
	v_cvt_pk_bf16_f32 v119, v128, v129
	v_cmp_lt_f32_e32 vcc, s33, v98
	s_nop 0
	v_mfma_f32_32x32x16_bf16 v[82:97], v[224:227], v[116:119], v[82:97]
	v_mfma_f32_32x32x16_bf16 v[66:81], v[228:231], v[116:119], v[66:81]
	v_fma_f32 v118, v98, s96, v162
	v_fma_f32 v119, v99, s96, v162
	v_fma_f32 v120, v100, s96, v162
	v_fma_f32 v121, v101, s96, v162
	v_exp_f32_e32 v118, v118
	v_exp_f32_e32 v119, v119
	v_pk_add_f32 v[116:117], v[182:183], v[180:181]
	v_cndmask_b32_e32 v98, 0, v118, vcc
	v_cmp_lt_f32_e32 vcc, s33, v99
	v_pk_add_f32 v[116:117], v[124:125], v[116:117]
	v_cndmask_b32_e64 v118, v118, v98, s[8:9]
	v_cndmask_b32_e32 v99, 0, v119, vcc
	v_cndmask_b32_e64 v119, v119, v99, s[8:9]
	v_exp_f32_e32 v99, v120
	v_exp_f32_e32 v120, v121
	v_cmp_lt_f32_e32 vcc, s33, v100
	v_cvt_pk_bf16_f32 v98, v118, v119
	v_pk_add_f32 v[116:117], v[126:127], v[116:117]
	v_cndmask_b32_e32 v100, 0, v99, vcc
	v_cmp_lt_f32_e32 vcc, s33, v101
	v_pk_add_f32 v[116:117], v[128:129], v[116:117]
	s_nop 0
	v_cndmask_b32_e32 v101, 0, v120, vcc
	v_cndmask_b32_e64 v121, v120, v101, s[8:9]
	v_cndmask_b32_e64 v120, v99, v100, s[8:9]
	v_pk_fma_f32 v[100:101], v[102:103], s[96:97], v[162:163] op_sel_hi:[1,0,0]
	v_cmp_lt_f32_e32 vcc, s33, v102
	v_exp_f32_e32 v100, v100
	v_exp_f32_e32 v101, v101
	v_cvt_pk_bf16_f32 v99, v120, v121
	v_cndmask_b32_e32 v102, 0, v100, vcc
	v_cmp_lt_f32_e32 vcc, s33, v103
	v_cndmask_b32_e64 v122, v100, v102, s[8:9]
	s_nop 0
	v_cndmask_b32_e32 v103, 0, v101, vcc
	v_cndmask_b32_e64 v123, v101, v103, s[8:9]
	v_pk_fma_f32 v[102:103], v[104:105], s[96:97], v[162:163] op_sel_hi:[1,0,0]
	v_cmp_lt_f32_e32 vcc, s33, v104
	v_exp_f32_e32 v101, v102
	v_exp_f32_e32 v102, v103
	v_cvt_pk_bf16_f32 v100, v122, v123
	v_cndmask_b32_e32 v103, 0, v101, vcc
	v_cmp_lt_f32_e32 vcc, s33, v105
	v_cndmask_b32_e64 v124, v101, v103, s[8:9]
	s_nop 0
	v_cndmask_b32_e32 v104, 0, v102, vcc
	v_cndmask_b32_e64 v125, v102, v104, s[8:9]
	s_nop 0
	v_cvt_pk_bf16_f32 v101, v124, v125
	v_cmp_lt_f32_e32 vcc, s33, v106
	s_waitcnt lgkmcnt(0)
; #define MFMA(a, b, c) __builtin_amdgcn_mfma_f32_32x32x16_bf16((a), (b), (c), 0, 0, 0)
;     ...
;         rs2 += pv;
;         pf.u[j] = __builtin_bit_cast(unsigned, __builtin_convertvector(pv, hwbf16x2));
;       }
; #pragma unroll
;       for (int d = 0; d < DV / 32; ++d) {
;         const char* vp = base + C::KBYTES + (d * 32 + lr) * C::VSTR + (ks * 32 + 16 * st + 4 * lh) * 2;
;         const s16x4 lo = *(const s16x4*)vp, hi = *(const s16x4*)(vp + 16);
;         const bf16x8 vf = __builtin_shufflevector(lo, hi, 0, 1, 2, 3, 4, 5, 6, 7);
;         O[d] = MFMA(vf, pf.v, O[d]);
;       }
;     }
;   float rs = rs2.x + rs2.y;
;   rs += __shfl_xor(rs, 32);
;   l += rs;
;     ...
;     if (t + NST - 1 < ntile) {
;       const int sn = (stage == 0) ? NST - 1 : stage - 1;
;       FA_ISSUE(t + NST - 1, sn)
;     }
	v_mfma_f32_32x32x16_bf16 v[82:97], v[232:235], v[98:101], v[82:97]
	s_nop 0
	s_waitcnt lgkmcnt(0)
	v_mfma_f32_32x32x16_bf16 v[66:81], v[236:239], v[98:101], v[66:81]
	v_add_f32_e64 v98, v118, v116
	v_add_f32_e64 v99, v119, v117
	v_add_f32_e64 v98, v120, v98
	v_add_f32_e64 v99, v121, v99
	v_add_f32_e64 v98, v122, v98
	v_add_f32_e64 v99, v123, v99
	v_pk_add_f32 v[116:117], v[124:125], v[98:99]
	v_pk_fma_f32 v[98:99], v[106:107], s[96:97], v[162:163] op_sel_hi:[1,0,0]
	s_nop 0
	v_exp_f32_e32 v98, v98
	v_exp_f32_e32 v99, v99
	v_cndmask_b32_e32 v100, 0, v98, vcc
	v_cmp_lt_f32_e32 vcc, s33, v107
	v_cndmask_b32_e64 v106, v98, v100, s[8:9]
	s_nop 0
	v_cndmask_b32_e32 v101, 0, v99, vcc
	v_cndmask_b32_e64 v107, v99, v101, s[8:9]
	v_pk_fma_f32 v[100:101], v[108:109], s[96:97], v[162:163] op_sel_hi:[1,0,0]
	v_cmp_lt_f32_e32 vcc, s33, v108
	v_exp_f32_e32 v99, v100
	v_exp_f32_e32 v100, v101
	v_cvt_pk_bf16_f32 v98, v106, v107
	v_cndmask_b32_e32 v101, 0, v99, vcc
	v_cmp_lt_f32_e32 vcc, s33, v109
	v_cndmask_b32_e64 v108, v99, v101, s[8:9]
	s_nop 0
	v_cndmask_b32_e32 v102, 0, v100, vcc
	v_cndmask_b32_e64 v109, v100, v102, s[8:9]
	v_pk_fma_f32 v[100:101], v[110:111], s[96:97], v[162:163] op_sel_hi:[1,0,0]
	v_cmp_lt_f32_e32 vcc, s33, v110
	v_exp_f32_e32 v100, v100
	v_exp_f32_e32 v101, v101
	v_cvt_pk_bf16_f32 v99, v108, v109
	v_cndmask_b32_e32 v102, 0, v100, vcc
	v_cmp_lt_f32_e32 vcc, s33, v111
	v_cndmask_b32_e64 v110, v100, v102, s[8:9]
	s_nop 0
	v_cndmask_b32_e32 v103, 0, v101, vcc
	v_cndmask_b32_e64 v111, v101, v103, s[8:9]
	v_pk_fma_f32 v[102:103], v[112:113], s[96:97], v[162:163] op_sel_hi:[1,0,0]
	v_cmp_lt_f32_e32 vcc, s33, v112
	v_exp_f32_e32 v101, v102
	v_exp_f32_e32 v102, v103
	v_cvt_pk_bf16_f32 v100, v110, v111
	v_cndmask_b32_e32 v103, 0, v101, vcc
	v_cmp_lt_f32_e32 vcc, s33, v113
	v_cndmask_b32_e64 v112, v101, v103, s[8:9]
	s_nop 0
	v_cndmask_b32_e32 v104, 0, v102, vcc
	v_cndmask_b32_e64 v113, v102, v104, s[8:9]
	s_nop 0
	v_cvt_pk_bf16_f32 v101, v112, v113
	s_nop 1
	v_mfma_f32_32x32x16_bf16 v[82:97], v[240:243], v[98:101], v[82:97]
	s_nop 0
	s_waitcnt lgkmcnt(0)
	v_mfma_f32_32x32x16_bf16 v[66:81], v[244:247], v[98:101], v[66:81]
	v_add_f32_e64 v98, v106, v116
	v_add_f32_e64 v99, v107, v117
	v_add_f32_e64 v98, v108, v98
	v_add_f32_e64 v99, v109, v99
	v_add_f32_e64 v98, v110, v98
	v_add_f32_e64 v99, v111, v99
	v_pk_add_f32 v[98:99], v[112:113], v[98:99]
	s_nop 0
	v_add_f32_e32 v98, v98, v99
	ds_bpermute_b32 v99, v165, v98
	s_cmp_gt_u32 s19, 5
	s_cbranch_scc1 .Ldma_m_win1
	s_add_i32 s98, s0, 0xffffb800
	s_cmp_lg_u32 s21, 0
	s_cselect_b32 s98, s98, 0xd800
	s_add_i32 s98, s98, 0
	v_add_u32_e32 v247, s98, v170
	s_nop 0
	v_readfirstlane_b32 s99, v247
	v_add_u32_e32 v247, s98, v169
	s_mov_b32 m0, s99
	v_readfirstlane_b32 s99, v247
	v_add_u32_e32 v247, s98, v171
	global_load_lds_dwordx4 v[160:161], off
	s_mov_b32 m0, s99
	v_readfirstlane_b32 s98, v247
	global_load_lds_dwordx4 v[158:159], off
	s_mov_b32 m0, s98
	s_nop 0
	global_load_lds_dwordx4 v[156:157], off

; #define MFMA(a, b, c) __builtin_amdgcn_mfma_f32_32x32x16_bf16((a), (b), (c), 0, 0, 0)
;     ...
;   float mc = m * c2;
;   if (MODE == 2) mc = selbit ? mc : 1e30f;
;   const f32x2v c2v = {c2, c2}, mcv = {-mc, -mc};
;   f32x2v rs2 = {0.f, 0.f};
; #pragma unroll
;   for (int ks = 0; ks < 2; ++ks)
; #pragma unroll
;     for (int st = 0; st < 2; ++st) {
;       union { unsigned u[4]; bf16x8 v; } pf;
; #pragma unroll
;       for (int j = 0; j < 4; ++j) {
;         const int i0 = 8 * st + 2 * j;
;         f32x2v t = {S[ks][i0], S[ks][i0 + 1]};
;         t = __builtin_elementwise_fma(t, c2v, mcv);
;         f32x2v pv;
;         if (variant == 1) { pv = t; } else {
;         pv.x = __builtin_amdgcn_exp2f(t.x);
;         pv.y = __builtin_amdgcn_exp2f(t.y);
;         }
;         if (MODE != 0) {
;           if (need_mask) {
;             pv.x = (S[ks][i0] > -1e29f) ? pv.x : 0.f;
;             pv.y = (S[ks][i0 + 1] > -1e29f) ? pv.y : 0.f;
;           }
;         }
;         rs2 += pv;
;         pf.u[j] = __builtin_bit_cast(unsigned, __builtin_convertvector(pv, hwbf16x2));
;       }
; #pragma unroll
;       for (int d = 0; d < DV / 32; ++d) {
;         const char* vp = base + C::KBYTES + (d * 32 + lr) * C::VSTR + (ks * 32 + 16 * st + 4 * lh) * 2;
;         const s16x4 lo = *(const s16x4*)vp, hi = *(const s16x4*)(vp + 16);
;         const bf16x8 vf = __builtin_shufflevector(lo, hi, 0, 1, 2, 3, 4, 5, 6, 7);
;         O[d] = MFMA(vf, pf.v, O[d]);
;       }
;     }
;   float rs = rs2.x + rs2.y;
;   rs += __shfl_xor(rs, 32);
;   l += rs;
;     ...
;     if (t + NST - 1 < ntile) {
;       const int sn = (stage == 0) ? NST - 1 : stage - 1;
;       FA_ISSUE(t + NST - 1, sn)
;     }
.Lfast_win1:
	v_mul_f32_e32 v162, 0xbe38aa3b, v162
	v_pk_fma_f32 v[180:181], v[114:115], s[96:97], v[162:163] op_sel_hi:[1,0,0]
	v_exp_f32_e32 v188, v180
	v_exp_f32_e32 v189, v181
	v_pk_fma_f32 v[114:115], v[116:117], s[96:97], v[162:163] op_sel_hi:[1,0,0]
	v_exp_f32_e32 v190, v114
	v_exp_f32_e32 v191, v115
	v_cvt_pk_bf16_f32 v180, v188, v189
	v_pk_fma_f32 v[114:115], v[118:119], s[96:97], v[162:163] op_sel_hi:[1,0,0]
	v_exp_f32_e32 v192, v114
	v_exp_f32_e32 v193, v115
	v_cvt_pk_bf16_f32 v181, v190, v191
	v_pk_fma_f32 v[114:115], v[120:121], s[96:97], v[162:163] op_sel_hi:[1,0,0]
	v_exp_f32_e32 v120, v114
	v_exp_f32_e32 v121, v115
	v_cvt_pk_bf16_f32 v182, v192, v193
	v_cvt_pk_bf16_f32 v183, v120, v121
	s_waitcnt lgkmcnt(0)
	s_nop 0
	v_mfma_f32_32x32x16_bf16 v[82:97], v[216:219], v[180:183], v[82:97]
	v_mfma_f32_32x32x16_bf16 v[66:81], v[220:223], v[180:183], v[66:81]
	v_add_f32_e64 v116, v188, 0
	v_add_f32_e64 v117, v189, 0
	v_add_f32_e64 v116, v190, v116
	v_add_f32_e64 v117, v191, v117
	v_add_f32_e64 v116, v192, v116
	v_add_f32_e64 v117, v193, v117
	v_pk_add_f32 v[180:181], v[120:121], v[116:117]
	v_pk_fma_f32 v[116:117], v[122:123], s[96:97], v[162:163] op_sel_hi:[1,0,0]
	v_exp_f32_e32 v182, v116
	v_exp_f32_e32 v183, v117
	v_pk_fma_f32 v[118:119], v[124:125], s[96:97], v[162:163] op_sel_hi:[1,0,0]
	v_exp_f32_e32 v124, v118
	v_exp_f32_e32 v125, v119
	v_cvt_pk_bf16_f32 v116, v182, v183
	v_pk_fma_f32 v[118:119], v[126:127], s[96:97], v[162:163] op_sel_hi:[1,0,0]
	v_exp_f32_e32 v126, v118
	v_exp_f32_e32 v127, v119
	v_cvt_pk_bf16_f32 v117, v124, v125
	v_pk_fma_f32 v[120:121], v[128:129], s[96:97], v[162:163] op_sel_hi:[1,0,0]
	v_exp_f32_e32 v128, v120
	v_exp_f32_e32 v129, v121
	v_cvt_pk_bf16_f32 v118, v126, v127
	v_cvt_pk_bf16_f32 v119, v128, v129
	s_nop 1
	v_mfma_f32_32x32x16_bf16 v[82:97], v[224:227], v[116:119], v[82:97]
	v_mfma_f32_32x32x16_bf16 v[66:81], v[228:231], v[116:119], v[66:81]
	v_fma_f32 v118, v98, s96, v162
	v_fma_f32 v119, v99, s96, v162
	v_fma_f32 v120, v100, s96, v162
	v_fma_f32 v121, v101, s96, v162
	v_exp_f32_e32 v118, v118
	v_exp_f32_e32 v119, v119
	v_pk_add_f32 v[116:117], v[182:183], v[180:181]
	v_pk_add_f32 v[116:117], v[124:125], v[116:117]
	v_exp_f32_e32 v120, v120
	v_exp_f32_e32 v121, v121
	v_cvt_pk_bf16_f32 v98, v118, v119
	v_pk_add_f32 v[116:117], v[126:127], v[116:117]
	v_pk_add_f32 v[116:117], v[128:129], v[116:117]
	v_pk_fma_f32 v[100:101], v[102:103], s[96:97], v[162:163] op_sel_hi:[1,0,0]
	v_exp_f32_e32 v122, v100
	v_exp_f32_e32 v123, v101
	v_cvt_pk_bf16_f32 v99, v120, v121
	v_pk_fma_f32 v[102:103], v[104:105], s[96:97], v[162:163] op_sel_hi:[1,0,0]
	v_exp_f32_e32 v124, v102
	v_exp_f32_e32 v125, v103
	v_cvt_pk_bf16_f32 v100, v122, v123
	v_cvt_pk_bf16_f32 v101, v124, v125
	s_nop 1
	v_mfma_f32_32x32x16_bf16 v[82:97], v[232:235], v[98:101], v[82:97]
	v_mfma_f32_32x32x16_bf16 v[66:81], v[236:239], v[98:101], v[66:81]
	v_add_f32_e64 v98, v118, v116
	v_add_f32_e64 v99, v119, v117
	v_add_f32_e64 v98, v120, v98
	v_add_f32_e64 v99, v121, v99
	v_add_f32_e64 v98, v122, v98
	v_add_f32_e64 v99, v123, v99
	v_pk_add_f32 v[116:117], v[124:125], v[98:99]
	v_pk_fma_f32 v[98:99], v[106:107], s[96:97], v[162:163] op_sel_hi:[1,0,0]
	v_exp_f32_e32 v106, v98
	v_exp_f32_e32 v107, v99
	v_pk_fma_f32 v[100:101], v[108:109], s[96:97], v[162:163] op_sel_hi:[1,0,0]
	v_exp_f32_e32 v108, v100
	v_exp_f32_e32 v109, v101
	v_cvt_pk_bf16_f32 v98, v106, v107
	v_pk_fma_f32 v[100:101], v[110:111], s[96:97], v[162:163] op_sel_hi:[1,0,0]
	v_exp_f32_e32 v110, v100
	v_exp_f32_e32 v111, v101
	v_cvt_pk_bf16_f32 v99, v108, v109
	v_pk_fma_f32 v[102:103], v[112:113], s[96:97], v[162:163] op_sel_hi:[1,0,0]
	v_exp_f32_e32 v112, v102
	v_exp_f32_e32 v113, v103
	v_cvt_pk_bf16_f32 v100, v110, v111
	v_cvt_pk_bf16_f32 v101, v112, v113
	s_nop 1
	v_mfma_f32_32x32x16_bf16 v[82:97], v[240:243], v[98:101], v[82:97]
	v_mfma_f32_32x32x16_bf16 v[66:81], v[244:247], v[98:101], v[66:81]
	v_add_f32_e64 v98, v106, v116
	v_add_f32_e64 v99, v107, v117
	v_add_f32_e64 v98, v108, v98
	v_add_f32_e64 v99, v109, v99
	v_add_f32_e64 v98, v110, v98
	v_add_f32_e64 v99, v111, v99
	v_pk_add_f32 v[98:99], v[112:113], v[98:99]
	v_add_f32_e32 v98, v98, v99
	ds_bpermute_b32 v99, v165, v98
	s_cmp_gt_u32 s19, 5
	s_cbranch_scc1 .Ldma_f_win1
	s_add_i32 s98, s0, 0xffffb800
	s_cmp_lg_u32 s21, 0
	s_cselect_b32 s98, s98, 0xd800
	s_add_i32 s98, s98, 0
	v_add_u32_e32 v247, s98, v170
	s_nop 0
	v_readfirstlane_b32 s99, v247
	v_add_u32_e32 v247, s98, v169
	s_mov_b32 m0, s99
	v_readfirstlane_b32 s99, v247
	v_add_u32_e32 v247, s98, v171
	global_load_lds_dwordx4 v[160:161], off
	s_mov_b32 m0, s99
	v_readfirstlane_b32 s98, v247
	global_load_lds_dwordx4 v[158:159], off
	s_mov_b32 m0, s98
	s_nop 0
	global_load_lds_dwordx4 v[156:157], off

; #define MFMA(a, b, c) __builtin_amdgcn_mfma_f32_32x32x16_bf16((a), (b), (c), 0, 0, 0)
;     ...
;   float mc = m * c2;
;   if (MODE == 2) mc = selbit ? mc : 1e30f;
;   const f32x2v c2v = {c2, c2}, mcv = {-mc, -mc};
;   f32x2v rs2 = {0.f, 0.f};
; #pragma unroll
;   for (int ks = 0; ks < 2; ++ks)
; #pragma unroll
;     for (int st = 0; st < 2; ++st) {
;       union { unsigned u[4]; bf16x8 v; } pf;
; #pragma unroll
;       for (int j = 0; j < 4; ++j) {
;         const int i0 = 8 * st + 2 * j;
;         f32x2v t = {S[ks][i0], S[ks][i0 + 1]};
;         t = __builtin_elementwise_fma(t, c2v, mcv);
;         f32x2v pv;
;         if (variant == 1) { pv = t; } else {
;         pv.x = __builtin_amdgcn_exp2f(t.x);
;         pv.y = __builtin_amdgcn_exp2f(t.y);
;         }
;         if (MODE != 0) {
;           if (need_mask) {
;             pv.x = (S[ks][i0] > -1e29f) ? pv.x : 0.f;
;             pv.y = (S[ks][i0 + 1] > -1e29f) ? pv.y : 0.f;
;           }
;         }
;         rs2 += pv;
;         pf.u[j] = __builtin_bit_cast(unsigned, __builtin_convertvector(pv, hwbf16x2));
;       }
; #pragma unroll
;       for (int d = 0; d < DV / 32; ++d) {
;         const char* vp = base + C::KBYTES + (d * 32 + lr) * C::VSTR + (ks * 32 + 16 * st + 4 * lh) * 2;
;         const s16x4 lo = *(const s16x4*)vp, hi = *(const s16x4*)(vp + 16);
;         const bf16x8 vf = __builtin_shufflevector(lo, hi, 0, 1, 2, 3, 4, 5, 6, 7);
;         O[d] = MFMA(vf, pf.v, O[d]);
;       }
;     }
.LBB0_487:
	s_cmp_eq_u64 s[8:9], 0
	s_cbranch_scc1 .Lfast_mla2
	v_mul_f32_e32 v104, 0xbe16c740, v104
	s_mov_b32 s12, 0x3e16c740
	v_pk_fma_f32 v[118:119], v[50:51], s[12:13], v[104:105] op_sel_hi:[1,0,0]
	v_cmp_lt_f32_e32 vcc, s33, v50
	v_exp_f32_e32 v117, v118
	v_exp_f32_e32 v118, v119
	v_cndmask_b32_e32 v50, 0, v117, vcc
	v_cmp_lt_f32_e32 vcc, s33, v51
	v_cndmask_b32_e64 v126, v117, v50, s[8:9]
	s_nop 0
	v_cndmask_b32_e32 v51, 0, v118, vcc
	v_cndmask_b32_e64 v127, v118, v51, s[8:9]
	v_pk_fma_f32 v[50:51], v[52:53], s[12:13], v[104:105] op_sel_hi:[1,0,0]
	v_cmp_lt_f32_e32 vcc, s33, v52
	v_exp_f32_e32 v50, v50
	v_exp_f32_e32 v51, v51
	v_cvt_pk_bf16_f32 v118, v126, v127
	v_cndmask_b32_e32 v52, 0, v50, vcc
	v_cmp_lt_f32_e32 vcc, s33, v53
	v_cndmask_b32_e64 v128, v50, v52, s[8:9]
	s_nop 0
	v_cndmask_b32_e32 v53, 0, v51, vcc
	v_cndmask_b32_e64 v129, v51, v53, s[8:9]
	v_pk_fma_f32 v[50:51], v[54:55], s[12:13], v[104:105] op_sel_hi:[1,0,0]
	v_cmp_lt_f32_e32 vcc, s33, v54
	v_exp_f32_e32 v50, v50
	v_exp_f32_e32 v51, v51
	v_cvt_pk_bf16_f32 v119, v128, v129
	v_cndmask_b32_e32 v52, 0, v50, vcc
	v_cmp_lt_f32_e32 vcc, s33, v55
	v_cndmask_b32_e64 v130, v50, v52, s[8:9]
	s_nop 0
	v_cndmask_b32_e32 v53, 0, v51, vcc
	v_cndmask_b32_e64 v131, v51, v53, s[8:9]
	v_pk_fma_f32 v[50:51], v[56:57], s[12:13], v[104:105] op_sel_hi:[1,0,0]
	v_cmp_lt_f32_e32 vcc, s33, v56
	v_exp_f32_e32 v50, v50
	v_exp_f32_e32 v51, v51
	v_cvt_pk_bf16_f32 v120, v130, v131
	v_cndmask_b32_e32 v52, 0, v50, vcc
	v_cmp_lt_f32_e32 vcc, s33, v57
	v_cndmask_b32_e64 v56, v50, v52, s[8:9]
	s_nop 0
	v_cndmask_b32_e32 v53, 0, v51, vcc
	v_cndmask_b32_e64 v57, v51, v53, s[8:9]
	v_cvt_pk_bf16_f32 v121, v56, v57
	v_cmp_lt_f32_e32 vcc, s33, v58
	s_waitcnt lgkmcnt(0)
	v_mfma_f32_32x32x16_bf16 v[18:33], v[216:219], v[118:121], v[18:33]
	v_mfma_f32_32x32x16_bf16 v[2:17], v[220:223], v[118:121], v[2:17]
	v_add_f32_e64 v52, v126, 0
	v_add_f32_e64 v53, v127, 0
	v_add_f32_e64 v52, v128, v52
	v_add_f32_e64 v53, v129, v53
	v_add_f32_e64 v52, v130, v52
	v_add_f32_e64 v53, v131, v53
	v_pk_add_f32 v[118:119], v[56:57], v[52:53]
	v_pk_fma_f32 v[52:53], v[58:59], s[12:13], v[104:105] op_sel_hi:[1,0,0]
	s_nop 0
	v_exp_f32_e32 v52, v52
	v_exp_f32_e32 v53, v53
	v_cndmask_b32_e32 v54, 0, v52, vcc
	v_cmp_lt_f32_e32 vcc, s33, v59
	v_cndmask_b32_e64 v120, v52, v54, s[8:9]
	s_nop 0
	v_cndmask_b32_e32 v55, 0, v53, vcc
	v_cndmask_b32_e64 v121, v53, v55, s[8:9]
	v_pk_fma_f32 v[54:55], v[60:61], s[12:13], v[104:105] op_sel_hi:[1,0,0]
	v_cmp_lt_f32_e32 vcc, s33, v60
	v_exp_f32_e32 v53, v54
	v_exp_f32_e32 v54, v55
	v_cvt_pk_bf16_f32 v52, v120, v121
	v_cndmask_b32_e32 v55, 0, v53, vcc
	v_cmp_lt_f32_e32 vcc, s33, v61
	v_cndmask_b32_e64 v60, v53, v55, s[8:9]
	s_nop 0
	v_cndmask_b32_e32 v56, 0, v54, vcc
	v_cndmask_b32_e64 v61, v54, v56, s[8:9]
	v_pk_fma_f32 v[54:55], v[62:63], s[12:13], v[104:105] op_sel_hi:[1,0,0]
	v_cmp_lt_f32_e32 vcc, s33, v62
	v_exp_f32_e32 v54, v54
	v_exp_f32_e32 v55, v55
	v_cvt_pk_bf16_f32 v53, v60, v61
	v_cndmask_b32_e32 v56, 0, v54, vcc
	v_cmp_lt_f32_e32 vcc, s33, v63
	v_cndmask_b32_e64 v62, v54, v56, s[8:9]
	s_nop 0
	v_cndmask_b32_e32 v57, 0, v55, vcc
	v_cndmask_b32_e64 v63, v55, v57, s[8:9]
	v_pk_fma_f32 v[56:57], v[64:65], s[12:13], v[104:105] op_sel_hi:[1,0,0]
	v_cmp_lt_f32_e32 vcc, s33, v64
	v_exp_f32_e32 v55, v56
	v_exp_f32_e32 v56, v57
	v_cvt_pk_bf16_f32 v54, v62, v63
	v_cndmask_b32_e32 v57, 0, v55, vcc
	v_cmp_lt_f32_e32 vcc, s33, v65
	v_cndmask_b32_e64 v64, v55, v57, s[8:9]
	s_nop 0
	v_cndmask_b32_e32 v58, 0, v56, vcc
	v_cndmask_b32_e64 v65, v56, v58, s[8:9]
	v_cvt_pk_bf16_f32 v55, v64, v65
	v_cmp_lt_f32_e32 vcc, s33, v34
	s_nop 0
	v_mfma_f32_32x32x16_bf16 v[18:33], v[224:227], v[52:55], v[18:33]
	v_mfma_f32_32x32x16_bf16 v[2:17], v[228:231], v[52:55], v[2:17]
	v_fma_f32 v54, v34, s12, v104
	v_fma_f32 v55, v35, s12, v104
	v_fma_f32 v56, v36, s12, v104
	v_fma_f32 v57, v37, s12, v104
	v_exp_f32_e32 v54, v54
	v_exp_f32_e32 v55, v55
	v_pk_add_f32 v[52:53], v[120:121], v[118:119]
	v_cndmask_b32_e32 v34, 0, v54, vcc
	v_cmp_lt_f32_e32 vcc, s33, v35
	v_pk_add_f32 v[52:53], v[60:61], v[52:53]
	v_cndmask_b32_e64 v54, v54, v34, s[8:9]
	v_cndmask_b32_e32 v35, 0, v55, vcc
	v_cndmask_b32_e64 v55, v55, v35, s[8:9]
	v_exp_f32_e32 v35, v56
	v_exp_f32_e32 v56, v57
	v_cmp_lt_f32_e32 vcc, s33, v36
	v_cvt_pk_bf16_f32 v34, v54, v55
	v_pk_add_f32 v[52:53], v[62:63], v[52:53]
	v_cndmask_b32_e32 v36, 0, v35, vcc
	v_cmp_lt_f32_e32 vcc, s33, v37
	v_pk_add_f32 v[52:53], v[64:65], v[52:53]
	s_nop 0
	v_cndmask_b32_e32 v37, 0, v56, vcc
	v_cndmask_b32_e64 v57, v56, v37, s[8:9]
	v_cndmask_b32_e64 v56, v35, v36, s[8:9]
	v_pk_fma_f32 v[36:37], v[38:39], s[12:13], v[104:105] op_sel_hi:[1,0,0]
	v_cmp_lt_f32_e32 vcc, s33, v38
	v_exp_f32_e32 v36, v36
	v_exp_f32_e32 v37, v37
	v_cvt_pk_bf16_f32 v35, v56, v57
	v_cndmask_b32_e32 v38, 0, v36, vcc
	v_cmp_lt_f32_e32 vcc, s33, v39
	v_cndmask_b32_e64 v58, v36, v38, s[8:9]
	s_nop 0
	v_cndmask_b32_e32 v39, 0, v37, vcc
	v_cndmask_b32_e64 v59, v37, v39, s[8:9]
	v_pk_fma_f32 v[38:39], v[40:41], s[12:13], v[104:105] op_sel_hi:[1,0,0]
	v_cmp_lt_f32_e32 vcc, s33, v40
	v_exp_f32_e32 v37, v38
	v_exp_f32_e32 v38, v39
	v_cvt_pk_bf16_f32 v36, v58, v59
	v_cndmask_b32_e32 v39, 0, v37, vcc
	v_cmp_lt_f32_e32 vcc, s33, v41
	v_cndmask_b32_e64 v60, v37, v39, s[8:9]
	s_nop 0
	v_cndmask_b32_e32 v40, 0, v38, vcc
	v_cndmask_b32_e64 v61, v38, v40, s[8:9]
	v_cvt_pk_bf16_f32 v37, v60, v61
	v_cmp_lt_f32_e32 vcc, s33, v42
	s_waitcnt lgkmcnt(0)
; #define MFMA(a, b, c) __builtin_amdgcn_mfma_f32_32x32x16_bf16((a), (b), (c), 0, 0, 0)
;     ...
;         rs2 += pv;
;         pf.u[j] = __builtin_bit_cast(unsigned, __builtin_convertvector(pv, hwbf16x2));
;       }
; #pragma unroll
;       for (int d = 0; d < DV / 32; ++d) {
;         const char* vp = base + C::KBYTES + (d * 32 + lr) * C::VSTR + (ks * 32 + 16 * st + 4 * lh) * 2;
;         const s16x4 lo = *(const s16x4*)vp, hi = *(const s16x4*)(vp + 16);
;         const bf16x8 vf = __builtin_shufflevector(lo, hi, 0, 1, 2, 3, 4, 5, 6, 7);
;         O[d] = MFMA(vf, pf.v, O[d]);
;       }
;     }
;   float rs = rs2.x + rs2.y;
;   rs += __shfl_xor(rs, 32);
;   l += rs;
;     ...
;     if (t + NST - 1 < ntile) {
;       const int sn = (stage == 0) ? NST - 1 : stage - 1;
;       FA_ISSUE(t + NST - 1, sn)
;     }
	v_mfma_f32_32x32x16_bf16 v[18:33], v[232:235], v[34:37], v[18:33]
	v_mfma_f32_32x32x16_bf16 v[2:17], v[236:239], v[34:37], v[2:17]
	v_add_f32_e64 v34, v54, v52
	v_add_f32_e64 v35, v55, v53
	v_add_f32_e64 v34, v56, v34
	v_add_f32_e64 v35, v57, v35
	v_add_f32_e64 v34, v58, v34
	v_add_f32_e64 v35, v59, v35
	v_pk_add_f32 v[52:53], v[60:61], v[34:35]
	v_pk_fma_f32 v[34:35], v[42:43], s[12:13], v[104:105] op_sel_hi:[1,0,0]
	s_nop 0
	v_exp_f32_e32 v34, v34
	v_exp_f32_e32 v35, v35
	v_cndmask_b32_e32 v36, 0, v34, vcc
	v_cmp_lt_f32_e32 vcc, s33, v43
	v_cndmask_b32_e64 v42, v34, v36, s[8:9]
	s_nop 0
	v_cndmask_b32_e32 v37, 0, v35, vcc
	v_cndmask_b32_e64 v43, v35, v37, s[8:9]
	v_pk_fma_f32 v[36:37], v[44:45], s[12:13], v[104:105] op_sel_hi:[1,0,0]
	v_cmp_lt_f32_e32 vcc, s33, v44
	v_exp_f32_e32 v35, v36
	v_exp_f32_e32 v36, v37
	v_cvt_pk_bf16_f32 v34, v42, v43
	v_cndmask_b32_e32 v37, 0, v35, vcc
	v_cmp_lt_f32_e32 vcc, s33, v45
	v_cndmask_b32_e64 v44, v35, v37, s[8:9]
	s_nop 0
	v_cndmask_b32_e32 v38, 0, v36, vcc
	v_cndmask_b32_e64 v45, v36, v38, s[8:9]
	v_pk_fma_f32 v[36:37], v[46:47], s[12:13], v[104:105] op_sel_hi:[1,0,0]
	v_cmp_lt_f32_e32 vcc, s33, v46
	v_exp_f32_e32 v36, v36
	v_exp_f32_e32 v37, v37
	v_cvt_pk_bf16_f32 v35, v44, v45
	v_cndmask_b32_e32 v38, 0, v36, vcc
	v_cmp_lt_f32_e32 vcc, s33, v47
	v_cndmask_b32_e64 v46, v36, v38, s[8:9]
	s_nop 0
	v_cndmask_b32_e32 v39, 0, v37, vcc
	v_cndmask_b32_e64 v47, v37, v39, s[8:9]
	v_pk_fma_f32 v[38:39], v[48:49], s[12:13], v[104:105] op_sel_hi:[1,0,0]
	v_cmp_lt_f32_e32 vcc, s33, v48
	v_exp_f32_e32 v37, v38
	v_exp_f32_e32 v38, v39
	v_cvt_pk_bf16_f32 v36, v46, v47
	v_cndmask_b32_e32 v39, 0, v37, vcc
	v_cmp_lt_f32_e32 vcc, s33, v49
	v_cndmask_b32_e64 v48, v37, v39, s[8:9]
	s_nop 0
	v_cndmask_b32_e32 v40, 0, v38, vcc
	v_cndmask_b32_e64 v49, v38, v40, s[8:9]
	v_cvt_pk_bf16_f32 v37, v48, v49
	s_nop 1
	v_mfma_f32_32x32x16_bf16 v[18:33], v[240:243], v[34:37], v[18:33]
	v_mfma_f32_32x32x16_bf16 v[2:17], v[244:247], v[34:37], v[2:17]
	v_add_f32_e64 v34, v42, v52
	v_add_f32_e64 v35, v43, v53
	v_add_f32_e64 v34, v44, v34
	v_add_f32_e64 v35, v45, v35
	v_add_f32_e64 v34, v46, v34
	v_add_f32_e64 v35, v47, v35
	v_pk_add_f32 v[34:35], v[48:49], v[34:35]
	s_nop 0
	v_add_f32_e32 v34, v34, v35
	ds_bpermute_b32 v35, v165, v34
	s_cmp_ge_u32 s17, s18
	s_cbranch_scc1 .Ldma_m_mla2
	s_add_i32 s98, s6, 0xffffa800
	s_cmp_lg_u32 s44, 0
	s_cselect_b32 s98, s98, 0x10800
	s_add_i32 s98, s98, 0
	v_add_u32_e32 v247, s98, v107
	s_nop 0
	v_readfirstlane_b32 s99, v247
	v_add_u32_e32 v247, s98, v93
	s_mov_b32 m0, s99
	v_readfirstlane_b32 s99, v247
	v_add_u32_e32 v247, s98, v108
	global_load_lds_dwordx4 v[102:103], off
	s_mov_b32 m0, s99
	v_readfirstlane_b32 s98, v247
	global_load_lds_dwordx4 v[100:101], off
	s_mov_b32 m0, s98
	s_nop 0
	global_load_lds_dwordx4 v[98:99], off

; #define MFMA(a, b, c) __builtin_amdgcn_mfma_f32_32x32x16_bf16((a), (b), (c), 0, 0, 0)
;     ...
;   float mc = m * c2;
;   if (MODE == 2) mc = selbit ? mc : 1e30f;
;   const f32x2v c2v = {c2, c2}, mcv = {-mc, -mc};
;   f32x2v rs2 = {0.f, 0.f};
; #pragma unroll
;   for (int ks = 0; ks < 2; ++ks)
; #pragma unroll
;     for (int st = 0; st < 2; ++st) {
;       union { unsigned u[4]; bf16x8 v; } pf;
; #pragma unroll
;       for (int j = 0; j < 4; ++j) {
;         const int i0 = 8 * st + 2 * j;
;         f32x2v t = {S[ks][i0], S[ks][i0 + 1]};
;         t = __builtin_elementwise_fma(t, c2v, mcv);
;         f32x2v pv;
;         if (variant == 1) { pv = t; } else {
;         pv.x = __builtin_amdgcn_exp2f(t.x);
;         pv.y = __builtin_amdgcn_exp2f(t.y);
;         }
;         if (MODE != 0) {
;           if (need_mask) {
;             pv.x = (S[ks][i0] > -1e29f) ? pv.x : 0.f;
;             pv.y = (S[ks][i0 + 1] > -1e29f) ? pv.y : 0.f;
;           }
;         }
;         rs2 += pv;
;         pf.u[j] = __builtin_bit_cast(unsigned, __builtin_convertvector(pv, hwbf16x2));
;       }
; #pragma unroll
;       for (int d = 0; d < DV / 32; ++d) {
;         const char* vp = base + C::KBYTES + (d * 32 + lr) * C::VSTR + (ks * 32 + 16 * st + 4 * lh) * 2;
;         const s16x4 lo = *(const s16x4*)vp, hi = *(const s16x4*)(vp + 16);
;         const bf16x8 vf = __builtin_shufflevector(lo, hi, 0, 1, 2, 3, 4, 5, 6, 7);
;         O[d] = MFMA(vf, pf.v, O[d]);
;       }
;     }
;   float rs = rs2.x + rs2.y;
;   rs += __shfl_xor(rs, 32);
;   l += rs;
;     ...
;     if (t + NST - 1 < ntile) {
;       const int sn = (stage == 0) ? NST - 1 : stage - 1;
;       FA_ISSUE(t + NST - 1, sn)
;     }
.Lfast_mla2:
	v_mul_f32_e32 v104, 0xbe16c740, v104
	s_mov_b32 s12, 0x3e16c740
	v_pk_fma_f32 v[118:119], v[50:51], s[12:13], v[104:105] op_sel_hi:[1,0,0]
	v_exp_f32_e32 v126, v118
	v_exp_f32_e32 v127, v119
	v_pk_fma_f32 v[50:51], v[52:53], s[12:13], v[104:105] op_sel_hi:[1,0,0]
	v_exp_f32_e32 v128, v50
	v_exp_f32_e32 v129, v51
	v_cvt_pk_bf16_f32 v118, v126, v127
	v_pk_fma_f32 v[50:51], v[54:55], s[12:13], v[104:105] op_sel_hi:[1,0,0]
	v_exp_f32_e32 v130, v50
	v_exp_f32_e32 v131, v51
	v_cvt_pk_bf16_f32 v119, v128, v129
	v_pk_fma_f32 v[50:51], v[56:57], s[12:13], v[104:105] op_sel_hi:[1,0,0]
	v_exp_f32_e32 v56, v50
	v_exp_f32_e32 v57, v51
	v_cvt_pk_bf16_f32 v120, v130, v131
	v_cvt_pk_bf16_f32 v121, v56, v57
	s_waitcnt lgkmcnt(0)
	s_nop 0
	v_mfma_f32_32x32x16_bf16 v[18:33], v[216:219], v[118:121], v[18:33]
	v_mfma_f32_32x32x16_bf16 v[2:17], v[220:223], v[118:121], v[2:17]
	v_add_f32_e64 v52, v126, 0
	v_add_f32_e64 v53, v127, 0
	v_add_f32_e64 v52, v128, v52
	v_add_f32_e64 v53, v129, v53
	v_add_f32_e64 v52, v130, v52
	v_add_f32_e64 v53, v131, v53
	v_pk_add_f32 v[118:119], v[56:57], v[52:53]
	v_pk_fma_f32 v[52:53], v[58:59], s[12:13], v[104:105] op_sel_hi:[1,0,0]
	v_exp_f32_e32 v120, v52
	v_exp_f32_e32 v121, v53
	v_pk_fma_f32 v[54:55], v[60:61], s[12:13], v[104:105] op_sel_hi:[1,0,0]
	v_exp_f32_e32 v60, v54
	v_exp_f32_e32 v61, v55
	v_cvt_pk_bf16_f32 v52, v120, v121
	v_pk_fma_f32 v[54:55], v[62:63], s[12:13], v[104:105] op_sel_hi:[1,0,0]
	v_exp_f32_e32 v62, v54
	v_exp_f32_e32 v63, v55
	v_cvt_pk_bf16_f32 v53, v60, v61
	v_pk_fma_f32 v[56:57], v[64:65], s[12:13], v[104:105] op_sel_hi:[1,0,0]
	v_exp_f32_e32 v64, v56
	v_exp_f32_e32 v65, v57
	v_cvt_pk_bf16_f32 v54, v62, v63
	v_cvt_pk_bf16_f32 v55, v64, v65
	s_nop 1
	v_mfma_f32_32x32x16_bf16 v[18:33], v[224:227], v[52:55], v[18:33]
	v_mfma_f32_32x32x16_bf16 v[2:17], v[228:231], v[52:55], v[2:17]
	v_fma_f32 v54, v34, s12, v104
	v_fma_f32 v55, v35, s12, v104
	v_fma_f32 v56, v36, s12, v104
	v_fma_f32 v57, v37, s12, v104
	v_exp_f32_e32 v54, v54
	v_exp_f32_e32 v55, v55
	v_pk_add_f32 v[52:53], v[120:121], v[118:119]
	v_pk_add_f32 v[52:53], v[60:61], v[52:53]
	v_exp_f32_e32 v56, v56
	v_exp_f32_e32 v57, v57
	v_cvt_pk_bf16_f32 v34, v54, v55
	v_pk_add_f32 v[52:53], v[62:63], v[52:53]
	v_pk_add_f32 v[52:53], v[64:65], v[52:53]
	v_pk_fma_f32 v[36:37], v[38:39], s[12:13], v[104:105] op_sel_hi:[1,0,0]
	v_exp_f32_e32 v58, v36
	v_exp_f32_e32 v59, v37
	v_cvt_pk_bf16_f32 v35, v56, v57
	v_pk_fma_f32 v[38:39], v[40:41], s[12:13], v[104:105] op_sel_hi:[1,0,0]
	v_exp_f32_e32 v60, v38
	v_exp_f32_e32 v61, v39
	v_cvt_pk_bf16_f32 v36, v58, v59
	v_cvt_pk_bf16_f32 v37, v60, v61
	s_nop 1
	v_mfma_f32_32x32x16_bf16 v[18:33], v[232:235], v[34:37], v[18:33]
	v_mfma_f32_32x32x16_bf16 v[2:17], v[236:239], v[34:37], v[2:17]
	v_add_f32_e64 v34, v54, v52
	v_add_f32_e64 v35, v55, v53
	v_add_f32_e64 v34, v56, v34
	v_add_f32_e64 v35, v57, v35
	v_add_f32_e64 v34, v58, v34
	v_add_f32_e64 v35, v59, v35
	v_pk_add_f32 v[52:53], v[60:61], v[34:35]
	v_pk_fma_f32 v[34:35], v[42:43], s[12:13], v[104:105] op_sel_hi:[1,0,0]
	v_exp_f32_e32 v42, v34
	v_exp_f32_e32 v43, v35
	v_pk_fma_f32 v[36:37], v[44:45], s[12:13], v[104:105] op_sel_hi:[1,0,0]
	v_exp_f32_e32 v44, v36
	v_exp_f32_e32 v45, v37
	v_cvt_pk_bf16_f32 v34, v42, v43
	v_pk_fma_f32 v[36:37], v[46:47], s[12:13], v[104:105] op_sel_hi:[1,0,0]
	v_exp_f32_e32 v46, v36
	v_exp_f32_e32 v47, v37
	v_cvt_pk_bf16_f32 v35, v44, v45
	v_pk_fma_f32 v[38:39], v[48:49], s[12:13], v[104:105] op_sel_hi:[1,0,0]
	v_exp_f32_e32 v48, v38
	v_exp_f32_e32 v49, v39
	v_cvt_pk_bf16_f32 v36, v46, v47
	v_cvt_pk_bf16_f32 v37, v48, v49
	s_nop 1
	v_mfma_f32_32x32x16_bf16 v[18:33], v[240:243], v[34:37], v[18:33]
	v_mfma_f32_32x32x16_bf16 v[2:17], v[244:247], v[34:37], v[2:17]
	v_add_f32_e64 v34, v42, v52
	v_add_f32_e64 v35, v43, v53
	v_add_f32_e64 v34, v44, v34
	v_add_f32_e64 v35, v45, v35
	v_add_f32_e64 v34, v46, v34
	v_add_f32_e64 v35, v47, v35
	v_pk_add_f32 v[34:35], v[48:49], v[34:35]
	v_add_f32_e32 v34, v34, v35
	ds_bpermute_b32 v35, v165, v34
	s_cmp_ge_u32 s17, s18
	s_cbranch_scc1 .Ldma_f_mla2
	s_add_i32 s98, s6, 0xffffa800
	s_cmp_lg_u32 s44, 0
	s_cselect_b32 s98, s98, 0x10800
	s_add_i32 s98, s98, 0
	v_add_u32_e32 v247, s98, v107
	s_nop 0
	v_readfirstlane_b32 s99, v247
	v_add_u32_e32 v247, s98, v93
	s_mov_b32 m0, s99
	v_readfirstlane_b32 s99, v247
	v_add_u32_e32 v247, s98, v108
	global_load_lds_dwordx4 v[102:103], off
	s_mov_b32 m0, s99
	v_readfirstlane_b32 s98, v247
	global_load_lds_dwordx4 v[100:101], off
	s_mov_b32 m0, s98
	s_nop 0
	global_load_lds_dwordx4 v[98:99], off

; #define MFMA(a, b, c) __builtin_amdgcn_mfma_f32_32x32x16_bf16((a), (b), (c), 0, 0, 0)
;     ...
;   float mc = m * c2;
;   if (MODE == 2) mc = selbit ? mc : 1e30f;
;   const f32x2v c2v = {c2, c2}, mcv = {-mc, -mc};
;   f32x2v rs2 = {0.f, 0.f};
; #pragma unroll
;   for (int ks = 0; ks < 2; ++ks)
; #pragma unroll
;     for (int st = 0; st < 2; ++st) {
;       union { unsigned u[4]; bf16x8 v; } pf;
; #pragma unroll
;       for (int j = 0; j < 4; ++j) {
;         const int i0 = 8 * st + 2 * j;
;         f32x2v t = {S[ks][i0], S[ks][i0 + 1]};
;         t = __builtin_elementwise_fma(t, c2v, mcv);
;         f32x2v pv;
;         if (variant == 1) { pv = t; } else {
;         pv.x = __builtin_amdgcn_exp2f(t.x);
;         pv.y = __builtin_amdgcn_exp2f(t.y);
;         }
;         if (MODE != 0) {
;           if (need_mask) {
;             pv.x = (S[ks][i0] > -1e29f) ? pv.x : 0.f;
;             pv.y = (S[ks][i0 + 1] > -1e29f) ? pv.y : 0.f;
;           }
;         }
;         rs2 += pv;
;         pf.u[j] = __builtin_bit_cast(unsigned, __builtin_convertvector(pv, hwbf16x2));
;       }
; #pragma unroll
;       for (int d = 0; d < DV / 32; ++d) {
;         const char* vp = base + C::KBYTES + (d * 32 + lr) * C::VSTR + (ks * 32 + 16 * st + 4 * lh) * 2;
;         const s16x4 lo = *(const s16x4*)vp, hi = *(const s16x4*)(vp + 16);
;         const bf16x8 vf = __builtin_shufflevector(lo, hi, 0, 1, 2, 3, 4, 5, 6, 7);
;         O[d] = MFMA(vf, pf.v, O[d]);
;       }
;     }
.LBB0_549:
	s_cmp_eq_u64 s[8:9], 0
	s_cbranch_scc1 .Lfast_sel2
	v_mul_f32_e32 v14, 0xbe38aa3b, v14
	v_cndmask_b32_e64 v14, v208, v14, s[10:11]
	v_pk_fma_f32 v[120:121], v[96:97], s[96:97], v[14:15] op_sel_hi:[1,0,0]
	v_cmp_lt_f32_e32 vcc, s33, v96
	v_exp_f32_e32 v119, v120
	v_exp_f32_e32 v120, v121
	v_cndmask_b32_e32 v96, 0, v119, vcc
	v_cmp_lt_f32_e32 vcc, s33, v97
	v_cndmask_b32_e64 v128, v119, v96, s[8:9]
	s_nop 0
	v_cndmask_b32_e32 v97, 0, v120, vcc
	v_cndmask_b32_e64 v129, v120, v97, s[8:9]
	v_pk_fma_f32 v[96:97], v[98:99], s[96:97], v[14:15] op_sel_hi:[1,0,0]
	v_cmp_lt_f32_e32 vcc, s33, v98
	v_exp_f32_e32 v96, v96
	v_exp_f32_e32 v97, v97
	v_cvt_pk_bf16_f32 v120, v128, v129
	v_cndmask_b32_e32 v98, 0, v96, vcc
	v_cmp_lt_f32_e32 vcc, s33, v99
	v_cndmask_b32_e64 v130, v96, v98, s[8:9]
	s_nop 0
	v_cndmask_b32_e32 v99, 0, v97, vcc
	v_cndmask_b32_e64 v131, v97, v99, s[8:9]
	v_pk_fma_f32 v[96:97], v[100:101], s[96:97], v[14:15] op_sel_hi:[1,0,0]
	v_cmp_lt_f32_e32 vcc, s33, v100
	v_exp_f32_e32 v96, v96
	v_exp_f32_e32 v97, v97
	v_cvt_pk_bf16_f32 v121, v130, v131
	v_cndmask_b32_e32 v98, 0, v96, vcc
	v_cmp_lt_f32_e32 vcc, s33, v101
	v_cndmask_b32_e64 v132, v96, v98, s[8:9]
	s_nop 0
	v_cndmask_b32_e32 v99, 0, v97, vcc
	v_cndmask_b32_e64 v133, v97, v99, s[8:9]
	v_pk_fma_f32 v[96:97], v[102:103], s[96:97], v[14:15] op_sel_hi:[1,0,0]
	v_cmp_lt_f32_e32 vcc, s33, v102
	v_exp_f32_e32 v96, v96
	v_exp_f32_e32 v97, v97
	v_cvt_pk_bf16_f32 v122, v132, v133
	v_cndmask_b32_e32 v98, 0, v96, vcc
	v_cmp_lt_f32_e32 vcc, s33, v103
	v_cndmask_b32_e64 v102, v96, v98, s[8:9]
	s_nop 0
	v_cndmask_b32_e32 v99, 0, v97, vcc
	v_cndmask_b32_e64 v103, v97, v99, s[8:9]
	s_nop 0
	s_nop 0
	s_nop 0
	s_nop 0
	v_cvt_pk_bf16_f32 v123, v102, v103
	s_nop 0
	v_cmp_lt_f32_e32 vcc, s33, v104
	s_waitcnt lgkmcnt(0)
	v_mfma_f32_32x32x16_bf16 v[64:79], v[216:219], v[120:123], v[64:79]
	s_nop 0
	s_waitcnt lgkmcnt(0)
	v_mfma_f32_32x32x16_bf16 v[48:63], v[220:223], v[120:123], v[48:63]
	v_add_f32_e64 v98, v128, 0
	v_add_f32_e64 v99, v129, 0
	v_add_f32_e64 v98, v130, v98
	v_add_f32_e64 v99, v131, v99
	v_add_f32_e64 v98, v132, v98
	v_add_f32_e64 v99, v133, v99
	v_pk_add_f32 v[120:121], v[102:103], v[98:99]
	v_pk_fma_f32 v[98:99], v[104:105], s[96:97], v[14:15] op_sel_hi:[1,0,0]
	s_nop 0
	v_exp_f32_e32 v98, v98
	v_exp_f32_e32 v99, v99
	v_cndmask_b32_e32 v100, 0, v98, vcc
	v_cmp_lt_f32_e32 vcc, s33, v105
	v_cndmask_b32_e64 v122, v98, v100, s[8:9]
	s_nop 0
	v_cndmask_b32_e32 v101, 0, v99, vcc
	v_cndmask_b32_e64 v123, v99, v101, s[8:9]
	v_pk_fma_f32 v[100:101], v[106:107], s[96:97], v[14:15] op_sel_hi:[1,0,0]
	v_cmp_lt_f32_e32 vcc, s33, v106
	v_exp_f32_e32 v99, v100
	v_exp_f32_e32 v100, v101
	v_cvt_pk_bf16_f32 v98, v122, v123
	v_cndmask_b32_e32 v101, 0, v99, vcc
	v_cmp_lt_f32_e32 vcc, s33, v107
	v_cndmask_b32_e64 v106, v99, v101, s[8:9]
	s_nop 0
	v_cndmask_b32_e32 v102, 0, v100, vcc
	v_cndmask_b32_e64 v107, v100, v102, s[8:9]
	v_pk_fma_f32 v[100:101], v[108:109], s[96:97], v[14:15] op_sel_hi:[1,0,0]
	v_cmp_lt_f32_e32 vcc, s33, v108
	v_exp_f32_e32 v100, v100
	v_exp_f32_e32 v101, v101
	v_cvt_pk_bf16_f32 v99, v106, v107
	v_cndmask_b32_e32 v102, 0, v100, vcc
	v_cmp_lt_f32_e32 vcc, s33, v109
	v_cndmask_b32_e64 v108, v100, v102, s[8:9]
	s_nop 0
	v_cndmask_b32_e32 v103, 0, v101, vcc
	v_cndmask_b32_e64 v109, v101, v103, s[8:9]
	v_pk_fma_f32 v[102:103], v[110:111], s[96:97], v[14:15] op_sel_hi:[1,0,0]
	v_cmp_lt_f32_e32 vcc, s33, v110
	v_exp_f32_e32 v101, v102
	v_exp_f32_e32 v102, v103
	v_cvt_pk_bf16_f32 v100, v108, v109
	v_cndmask_b32_e32 v103, 0, v101, vcc
	v_cmp_lt_f32_e32 vcc, s33, v111
	v_cndmask_b32_e64 v110, v101, v103, s[8:9]
	s_nop 0
	v_cndmask_b32_e32 v104, 0, v102, vcc
	v_cndmask_b32_e64 v111, v102, v104, s[8:9]
	s_nop 0
	v_cvt_pk_bf16_f32 v101, v110, v111
	v_cmp_lt_f32_e32 vcc, s33, v80
	s_nop 0
	v_mfma_f32_32x32x16_bf16 v[64:79], v[224:227], v[98:101], v[64:79]
	v_mfma_f32_32x32x16_bf16 v[48:63], v[228:231], v[98:101], v[48:63]
	v_fma_f32 v100, v80, s96, v14
	v_fma_f32 v101, v81, s96, v14
	v_fma_f32 v102, v82, s96, v14
	v_fma_f32 v103, v83, s96, v14
	v_exp_f32_e32 v100, v100
	v_exp_f32_e32 v101, v101
	v_pk_add_f32 v[98:99], v[122:123], v[120:121]
	v_cndmask_b32_e32 v80, 0, v100, vcc
	v_cmp_lt_f32_e32 vcc, s33, v81
	v_pk_add_f32 v[98:99], v[106:107], v[98:99]
	v_cndmask_b32_e64 v100, v100, v80, s[8:9]
	v_cndmask_b32_e32 v81, 0, v101, vcc
	v_cndmask_b32_e64 v101, v101, v81, s[8:9]
	v_exp_f32_e32 v81, v102
	v_exp_f32_e32 v102, v103
	v_cmp_lt_f32_e32 vcc, s33, v82
	v_cvt_pk_bf16_f32 v80, v100, v101
	v_pk_add_f32 v[98:99], v[108:109], v[98:99]
	v_cndmask_b32_e32 v82, 0, v81, vcc
	v_cmp_lt_f32_e32 vcc, s33, v83
	v_pk_add_f32 v[98:99], v[110:111], v[98:99]
	s_nop 0
	v_cndmask_b32_e32 v83, 0, v102, vcc
	v_cndmask_b32_e64 v103, v102, v83, s[8:9]
	v_cndmask_b32_e64 v102, v81, v82, s[8:9]
	v_pk_fma_f32 v[82:83], v[84:85], s[96:97], v[14:15] op_sel_hi:[1,0,0]
	v_cmp_lt_f32_e32 vcc, s33, v84
	v_exp_f32_e32 v82, v82
	v_exp_f32_e32 v83, v83
	v_cvt_pk_bf16_f32 v81, v102, v103
	v_cndmask_b32_e32 v84, 0, v82, vcc
	v_cmp_lt_f32_e32 vcc, s33, v85
	v_cndmask_b32_e64 v104, v82, v84, s[8:9]
	s_nop 0
	v_cndmask_b32_e32 v85, 0, v83, vcc
	v_cndmask_b32_e64 v105, v83, v85, s[8:9]
	v_pk_fma_f32 v[84:85], v[86:87], s[96:97], v[14:15] op_sel_hi:[1,0,0]
	v_cmp_lt_f32_e32 vcc, s33, v86
	v_exp_f32_e32 v83, v84
	v_exp_f32_e32 v84, v85
	v_cvt_pk_bf16_f32 v82, v104, v105
	v_cndmask_b32_e32 v85, 0, v83, vcc
	v_cmp_lt_f32_e32 vcc, s33, v87
	v_cndmask_b32_e64 v106, v83, v85, s[8:9]
	s_nop 0
	v_cndmask_b32_e32 v86, 0, v84, vcc
	v_cndmask_b32_e64 v107, v84, v86, s[8:9]
	s_nop 0
	v_cvt_pk_bf16_f32 v83, v106, v107
	v_cmp_lt_f32_e32 vcc, s33, v88
	s_waitcnt lgkmcnt(0)
; #define MFMA(a, b, c) __builtin_amdgcn_mfma_f32_32x32x16_bf16((a), (b), (c), 0, 0, 0)
;     ...
;         rs2 += pv;
;         pf.u[j] = __builtin_bit_cast(unsigned, __builtin_convertvector(pv, hwbf16x2));
;       }
; #pragma unroll
;       for (int d = 0; d < DV / 32; ++d) {
;         const char* vp = base + C::KBYTES + (d * 32 + lr) * C::VSTR + (ks * 32 + 16 * st + 4 * lh) * 2;
;         const s16x4 lo = *(const s16x4*)vp, hi = *(const s16x4*)(vp + 16);
;         const bf16x8 vf = __builtin_shufflevector(lo, hi, 0, 1, 2, 3, 4, 5, 6, 7);
;         O[d] = MFMA(vf, pf.v, O[d]);
;       }
;     }
;   float rs = rs2.x + rs2.y;
;   rs += __shfl_xor(rs, 32);
;   l += rs;
;     ...
;     if (t + NST - 1 < ntile) {
;       const int sn = (stage == 0) ? NST - 1 : stage - 1;
;       FA_ISSUE(t + NST - 1, sn)
;     }
	v_mfma_f32_32x32x16_bf16 v[64:79], v[232:235], v[80:83], v[64:79]
	s_nop 0
	s_waitcnt lgkmcnt(0)
	v_mfma_f32_32x32x16_bf16 v[48:63], v[236:239], v[80:83], v[48:63]
	v_add_f32_e64 v80, v100, v98
	v_add_f32_e64 v81, v101, v99
	v_add_f32_e64 v80, v102, v80
	v_add_f32_e64 v81, v103, v81
	v_add_f32_e64 v80, v104, v80
	v_add_f32_e64 v81, v105, v81
	v_pk_add_f32 v[98:99], v[106:107], v[80:81]
	v_pk_fma_f32 v[80:81], v[88:89], s[96:97], v[14:15] op_sel_hi:[1,0,0]
	s_nop 0
	v_exp_f32_e32 v80, v80
	v_exp_f32_e32 v81, v81
	v_cndmask_b32_e32 v82, 0, v80, vcc
	v_cmp_lt_f32_e32 vcc, s33, v89
	v_cndmask_b32_e64 v88, v80, v82, s[8:9]
	s_nop 0
	v_cndmask_b32_e32 v83, 0, v81, vcc
	v_cndmask_b32_e64 v89, v81, v83, s[8:9]
	v_pk_fma_f32 v[82:83], v[90:91], s[96:97], v[14:15] op_sel_hi:[1,0,0]
	v_cmp_lt_f32_e32 vcc, s33, v90
	v_exp_f32_e32 v81, v82
	v_exp_f32_e32 v82, v83
	v_cvt_pk_bf16_f32 v80, v88, v89
	v_cndmask_b32_e32 v83, 0, v81, vcc
	v_cmp_lt_f32_e32 vcc, s33, v91
	v_cndmask_b32_e64 v90, v81, v83, s[8:9]
	s_nop 0
	v_cndmask_b32_e32 v84, 0, v82, vcc
	v_cndmask_b32_e64 v91, v82, v84, s[8:9]
	v_pk_fma_f32 v[82:83], v[92:93], s[96:97], v[14:15] op_sel_hi:[1,0,0]
	v_cmp_lt_f32_e32 vcc, s33, v92
	v_exp_f32_e32 v82, v82
	v_exp_f32_e32 v83, v83
	v_cvt_pk_bf16_f32 v81, v90, v91
	v_cndmask_b32_e32 v84, 0, v82, vcc
	v_cmp_lt_f32_e32 vcc, s33, v93
	v_cndmask_b32_e64 v92, v82, v84, s[8:9]
	s_nop 0
	v_cndmask_b32_e32 v85, 0, v83, vcc
	v_cndmask_b32_e64 v93, v83, v85, s[8:9]
	v_pk_fma_f32 v[84:85], v[94:95], s[96:97], v[14:15] op_sel_hi:[1,0,0]
	v_cmp_lt_f32_e32 vcc, s33, v94
	v_exp_f32_e32 v14, v84
	v_exp_f32_e32 v83, v85
	v_cvt_pk_bf16_f32 v82, v92, v93
	v_cndmask_b32_e32 v84, 0, v14, vcc
	v_cmp_lt_f32_e32 vcc, s33, v95
	v_cndmask_b32_e64 v94, v14, v84, s[8:9]
	s_nop 0
	v_cndmask_b32_e32 v85, 0, v83, vcc
	v_cndmask_b32_e64 v95, v83, v85, s[8:9]
	s_nop 0
	v_cvt_pk_bf16_f32 v83, v94, v95
	s_nop 1
	v_mfma_f32_32x32x16_bf16 v[64:79], v[240:243], v[80:83], v[64:79]
	s_nop 0
	s_waitcnt lgkmcnt(0)
	v_mfma_f32_32x32x16_bf16 v[48:63], v[244:247], v[80:83], v[48:63]
	v_add_f32_e64 v80, v88, v98
	v_add_f32_e64 v81, v89, v99
	v_add_f32_e64 v80, v90, v80
	v_add_f32_e64 v81, v91, v81
	v_add_f32_e64 v80, v92, v80
	v_add_f32_e64 v81, v93, v81
	v_pk_add_f32 v[80:81], v[94:95], v[80:81]
	s_nop 0
	v_add_f32_e32 v14, v80, v81
	ds_bpermute_b32 v80, v165, v14
	s_add_i32 s98, s0, 3
	s_cmp_gt_u32 s98, s41
	s_cbranch_scc1 .Ldma_m_sel2
	s_add_i32 s98, s6, 0xffffb800
	s_cmp_lg_u32 s45, 0
	s_cselect_b32 s98, s98, 0xd800
	s_add_i32 s98, s98, 0
	v_add_u32_e32 v247, s98, v112
	s_nop 0
	v_readfirstlane_b32 s99, v247
	v_add_u32_e32 v247, s98, v15
	s_mov_b32 m0, s99
	v_readfirstlane_b32 s99, v247
	v_add_u32_e32 v247, s98, v113
	global_load_lds_dwordx4 v[12:13], off
	s_mov_b32 m0, s99
	v_readfirstlane_b32 s98, v247
	global_load_lds_dwordx4 v[10:11], off
	s_mov_b32 m0, s98
	s_nop 0
	global_load_lds_dwordx4 v[8:9], off

; #define MFMA(a, b, c) __builtin_amdgcn_mfma_f32_32x32x16_bf16((a), (b), (c), 0, 0, 0)
;     ...
;   float mc = m * c2;
;   if (MODE == 2) mc = selbit ? mc : 1e30f;
;   const f32x2v c2v = {c2, c2}, mcv = {-mc, -mc};
;   f32x2v rs2 = {0.f, 0.f};
; #pragma unroll
;   for (int ks = 0; ks < 2; ++ks)
; #pragma unroll
;     for (int st = 0; st < 2; ++st) {
;       union { unsigned u[4]; bf16x8 v; } pf;
; #pragma unroll
;       for (int j = 0; j < 4; ++j) {
;         const int i0 = 8 * st + 2 * j;
;         f32x2v t = {S[ks][i0], S[ks][i0 + 1]};
;         t = __builtin_elementwise_fma(t, c2v, mcv);
;         f32x2v pv;
;         if (variant == 1) { pv = t; } else {
;         pv.x = __builtin_amdgcn_exp2f(t.x);
;         pv.y = __builtin_amdgcn_exp2f(t.y);
;         }
;         if (MODE != 0) {
;           if (need_mask) {
;             pv.x = (S[ks][i0] > -1e29f) ? pv.x : 0.f;
;             pv.y = (S[ks][i0 + 1] > -1e29f) ? pv.y : 0.f;
;           }
;         }
;         rs2 += pv;
;         pf.u[j] = __builtin_bit_cast(unsigned, __builtin_convertvector(pv, hwbf16x2));
;       }
; #pragma unroll
;       for (int d = 0; d < DV / 32; ++d) {
;         const char* vp = base + C::KBYTES + (d * 32 + lr) * C::VSTR + (ks * 32 + 16 * st + 4 * lh) * 2;
;         const s16x4 lo = *(const s16x4*)vp, hi = *(const s16x4*)(vp + 16);
;         const bf16x8 vf = __builtin_shufflevector(lo, hi, 0, 1, 2, 3, 4, 5, 6, 7);
;         O[d] = MFMA(vf, pf.v, O[d]);
;       }
;     }
;   float rs = rs2.x + rs2.y;
;   rs += __shfl_xor(rs, 32);
;   l += rs;
;     ...
;     if (t + NST - 1 < ntile) {
;       const int sn = (stage == 0) ? NST - 1 : stage - 1;
;       FA_ISSUE(t + NST - 1, sn)
;     }
.Lfast_sel2:
	v_mul_f32_e32 v14, 0xbe38aa3b, v14
	v_cndmask_b32_e64 v14, v208, v14, s[10:11]
	v_pk_fma_f32 v[120:121], v[96:97], s[96:97], v[14:15] op_sel_hi:[1,0,0]
	v_exp_f32_e32 v128, v120
	v_exp_f32_e32 v129, v121
	v_pk_fma_f32 v[96:97], v[98:99], s[96:97], v[14:15] op_sel_hi:[1,0,0]
	v_exp_f32_e32 v130, v96
	v_exp_f32_e32 v131, v97
	v_cvt_pk_bf16_f32 v120, v128, v129
	v_pk_fma_f32 v[96:97], v[100:101], s[96:97], v[14:15] op_sel_hi:[1,0,0]
	v_exp_f32_e32 v132, v96
	v_exp_f32_e32 v133, v97
	v_cvt_pk_bf16_f32 v121, v130, v131
	v_pk_fma_f32 v[96:97], v[102:103], s[96:97], v[14:15] op_sel_hi:[1,0,0]
	v_exp_f32_e32 v102, v96
	v_exp_f32_e32 v103, v97
	v_cvt_pk_bf16_f32 v122, v132, v133
	v_cvt_pk_bf16_f32 v123, v102, v103
	s_waitcnt lgkmcnt(0)
	s_nop 0
	v_mfma_f32_32x32x16_bf16 v[64:79], v[216:219], v[120:123], v[64:79]
	v_mfma_f32_32x32x16_bf16 v[48:63], v[220:223], v[120:123], v[48:63]
	v_add_f32_e64 v98, v128, 0
	v_add_f32_e64 v99, v129, 0
	v_add_f32_e64 v98, v130, v98
	v_add_f32_e64 v99, v131, v99
	v_add_f32_e64 v98, v132, v98
	v_add_f32_e64 v99, v133, v99
	v_pk_add_f32 v[120:121], v[102:103], v[98:99]
	v_pk_fma_f32 v[98:99], v[104:105], s[96:97], v[14:15] op_sel_hi:[1,0,0]
	v_exp_f32_e32 v122, v98
	v_exp_f32_e32 v123, v99
	v_pk_fma_f32 v[100:101], v[106:107], s[96:97], v[14:15] op_sel_hi:[1,0,0]
	v_exp_f32_e32 v106, v100
	v_exp_f32_e32 v107, v101
	v_cvt_pk_bf16_f32 v98, v122, v123
	v_pk_fma_f32 v[100:101], v[108:109], s[96:97], v[14:15] op_sel_hi:[1,0,0]
	v_exp_f32_e32 v108, v100
	v_exp_f32_e32 v109, v101
	v_cvt_pk_bf16_f32 v99, v106, v107
	v_pk_fma_f32 v[102:103], v[110:111], s[96:97], v[14:15] op_sel_hi:[1,0,0]
	v_exp_f32_e32 v110, v102
	v_exp_f32_e32 v111, v103
	v_cvt_pk_bf16_f32 v100, v108, v109
	v_cvt_pk_bf16_f32 v101, v110, v111
	s_nop 1
	v_mfma_f32_32x32x16_bf16 v[64:79], v[224:227], v[98:101], v[64:79]
	v_mfma_f32_32x32x16_bf16 v[48:63], v[228:231], v[98:101], v[48:63]
	v_fma_f32 v100, v80, s96, v14
	v_fma_f32 v101, v81, s96, v14
	v_fma_f32 v102, v82, s96, v14
	v_fma_f32 v103, v83, s96, v14
	v_exp_f32_e32 v100, v100
	v_exp_f32_e32 v101, v101
	v_pk_add_f32 v[98:99], v[122:123], v[120:121]
	v_pk_add_f32 v[98:99], v[106:107], v[98:99]
	v_exp_f32_e32 v102, v102
	v_exp_f32_e32 v103, v103
	v_cvt_pk_bf16_f32 v80, v100, v101
	v_pk_add_f32 v[98:99], v[108:109], v[98:99]
	v_pk_add_f32 v[98:99], v[110:111], v[98:99]
	v_pk_fma_f32 v[82:83], v[84:85], s[96:97], v[14:15] op_sel_hi:[1,0,0]
	v_exp_f32_e32 v104, v82
	v_exp_f32_e32 v105, v83
	v_cvt_pk_bf16_f32 v81, v102, v103
	v_pk_fma_f32 v[84:85], v[86:87], s[96:97], v[14:15] op_sel_hi:[1,0,0]
	v_exp_f32_e32 v106, v84
	v_exp_f32_e32 v107, v85
	v_cvt_pk_bf16_f32 v82, v104, v105
	v_cvt_pk_bf16_f32 v83, v106, v107
	s_nop 1
	v_mfma_f32_32x32x16_bf16 v[64:79], v[232:235], v[80:83], v[64:79]
	v_mfma_f32_32x32x16_bf16 v[48:63], v[236:239], v[80:83], v[48:63]
	v_add_f32_e64 v80, v100, v98
	v_add_f32_e64 v81, v101, v99
	v_add_f32_e64 v80, v102, v80
	v_add_f32_e64 v81, v103, v81
	v_add_f32_e64 v80, v104, v80
	v_add_f32_e64 v81, v105, v81
	v_pk_add_f32 v[98:99], v[106:107], v[80:81]
	v_pk_fma_f32 v[80:81], v[88:89], s[96:97], v[14:15] op_sel_hi:[1,0,0]
	v_exp_f32_e32 v88, v80
	v_exp_f32_e32 v89, v81
	v_pk_fma_f32 v[82:83], v[90:91], s[96:97], v[14:15] op_sel_hi:[1,0,0]
	v_exp_f32_e32 v90, v82
	v_exp_f32_e32 v91, v83
	v_cvt_pk_bf16_f32 v80, v88, v89
	v_pk_fma_f32 v[82:83], v[92:93], s[96:97], v[14:15] op_sel_hi:[1,0,0]
	v_exp_f32_e32 v92, v82
	v_exp_f32_e32 v93, v83
	v_cvt_pk_bf16_f32 v81, v90, v91
	v_pk_fma_f32 v[84:85], v[94:95], s[96:97], v[14:15] op_sel_hi:[1,0,0]
	v_exp_f32_e32 v94, v84
	v_exp_f32_e32 v95, v85
	v_cvt_pk_bf16_f32 v82, v92, v93
	v_cvt_pk_bf16_f32 v83, v94, v95
	s_nop 1
	v_mfma_f32_32x32x16_bf16 v[64:79], v[240:243], v[80:83], v[64:79]
	v_mfma_f32_32x32x16_bf16 v[48:63], v[244:247], v[80:83], v[48:63]
	v_add_f32_e64 v80, v88, v98
	v_add_f32_e64 v81, v89, v99
	v_add_f32_e64 v80, v90, v80
	v_add_f32_e64 v81, v91, v81
	v_add_f32_e64 v80, v92, v80
	v_add_f32_e64 v81, v93, v81
	v_pk_add_f32 v[80:81], v[94:95], v[80:81]
	v_add_f32_e32 v14, v80, v81
	ds_bpermute_b32 v80, v165, v14
	s_add_i32 s98, s0, 3
	s_cmp_gt_u32 s98, s41
	s_cbranch_scc1 .Ldma_f_sel2
	s_add_i32 s98, s6, 0xffffb800
	s_cmp_lg_u32 s45, 0
	s_cselect_b32 s98, s98, 0xd800
	s_add_i32 s98, s98, 0
	v_add_u32_e32 v247, s98, v112
	s_nop 0
	v_readfirstlane_b32 s99, v247
	v_add_u32_e32 v247, s98, v15
	s_mov_b32 m0, s99
	v_readfirstlane_b32 s99, v247
	v_add_u32_e32 v247, s98, v113
	global_load_lds_dwordx4 v[12:13], off
	s_mov_b32 m0, s99
	v_readfirstlane_b32 s98, v247
	global_load_lds_dwordx4 v[10:11], off
	s_mov_b32 m0, s98
	s_nop 0
	global_load_lds_dwordx4 v[8:9], off

; #define MFMA(a, b, c) __builtin_amdgcn_mfma_f32_32x32x16_bf16((a), (b), (c), 0, 0, 0)
;     ...
;   float mc = m * c2;
;   if (MODE == 2) mc = selbit ? mc : 1e30f;
;   const f32x2v c2v = {c2, c2}, mcv = {-mc, -mc};
;   f32x2v rs2 = {0.f, 0.f};
; #pragma unroll
;   for (int ks = 0; ks < 2; ++ks)
; #pragma unroll
;     for (int st = 0; st < 2; ++st) {
;       union { unsigned u[4]; bf16x8 v; } pf;
; #pragma unroll
;       for (int j = 0; j < 4; ++j) {
;         const int i0 = 8 * st + 2 * j;
;         f32x2v t = {S[ks][i0], S[ks][i0 + 1]};
;         t = __builtin_elementwise_fma(t, c2v, mcv);
;         f32x2v pv;
;         if (variant == 1) { pv = t; } else {
;         pv.x = __builtin_amdgcn_exp2f(t.x);
;         pv.y = __builtin_amdgcn_exp2f(t.y);
;         }
;         if (MODE != 0) {
;           if (need_mask) {
;             pv.x = (S[ks][i0] > -1e29f) ? pv.x : 0.f;
;             pv.y = (S[ks][i0 + 1] > -1e29f) ? pv.y : 0.f;
;           }
;         }
;         rs2 += pv;
;         pf.u[j] = __builtin_bit_cast(unsigned, __builtin_convertvector(pv, hwbf16x2));
;       }
; #pragma unroll
;       for (int d = 0; d < DV / 32; ++d) {
;         const char* vp = base + C::KBYTES + (d * 32 + lr) * C::VSTR + (ks * 32 + 16 * st + 4 * lh) * 2;
;         const s16x4 lo = *(const s16x4*)vp, hi = *(const s16x4*)(vp + 16);
;         const bf16x8 vf = __builtin_shufflevector(lo, hi, 0, 1, 2, 3, 4, 5, 6, 7);
;         O[d] = MFMA(vf, pf.v, O[d]);
;       }
;     }
.LBB0_585:
	s_cmp_eq_u64 s[8:9], 0
	s_cbranch_scc1 .Lfast_win2
	v_mul_f32_e32 v12, 0xbe38aa3b, v12
	v_pk_fma_f32 v[176:177], v[128:129], s[96:97], v[12:13] op_sel_hi:[1,0,0]
	v_cmp_lt_f32_e32 vcc, s33, v128
	v_exp_f32_e32 v176, v176
	v_exp_f32_e32 v177, v177
	v_cndmask_b32_e32 v128, 0, v176, vcc
	v_cmp_lt_f32_e32 vcc, s33, v129
	v_cndmask_b32_e64 v184, v176, v128, s[8:9]
	s_nop 0
	v_cndmask_b32_e32 v129, 0, v177, vcc
	v_cndmask_b32_e64 v185, v177, v129, s[8:9]
	v_pk_fma_f32 v[128:129], v[130:131], s[96:97], v[12:13] op_sel_hi:[1,0,0]
	v_cmp_lt_f32_e32 vcc, s33, v130
	v_exp_f32_e32 v128, v128
	v_exp_f32_e32 v129, v129
	v_cvt_pk_bf16_f32 v176, v184, v185
	v_cndmask_b32_e32 v130, 0, v128, vcc
	v_cmp_lt_f32_e32 vcc, s33, v131
	v_cndmask_b32_e64 v186, v128, v130, s[8:9]
	s_nop 0
	v_cndmask_b32_e32 v131, 0, v129, vcc
	v_cndmask_b32_e64 v187, v129, v131, s[8:9]
	v_pk_fma_f32 v[128:129], v[132:133], s[96:97], v[12:13] op_sel_hi:[1,0,0]
	v_cmp_lt_f32_e32 vcc, s33, v132
	v_exp_f32_e32 v128, v128
	v_exp_f32_e32 v129, v129
	v_cvt_pk_bf16_f32 v177, v186, v187
	v_cndmask_b32_e32 v130, 0, v128, vcc
	v_cmp_lt_f32_e32 vcc, s33, v133
	v_cndmask_b32_e64 v188, v128, v130, s[8:9]
	s_nop 0
	v_cndmask_b32_e32 v131, 0, v129, vcc
	v_cndmask_b32_e64 v189, v129, v131, s[8:9]
	v_pk_fma_f32 v[128:129], v[134:135], s[96:97], v[12:13] op_sel_hi:[1,0,0]
	v_cmp_lt_f32_e32 vcc, s33, v134
	v_exp_f32_e32 v128, v128
	v_exp_f32_e32 v129, v129
	v_cvt_pk_bf16_f32 v178, v188, v189
	v_cndmask_b32_e32 v130, 0, v128, vcc
	v_cmp_lt_f32_e32 vcc, s33, v135
	v_cndmask_b32_e64 v134, v128, v130, s[8:9]
	s_nop 0
	v_cndmask_b32_e32 v131, 0, v129, vcc
	v_cndmask_b32_e64 v135, v129, v131, s[8:9]
	s_nop 0
	s_nop 0
	s_nop 0
	s_nop 0
	v_cvt_pk_bf16_f32 v179, v134, v135
	s_nop 0
	v_cmp_lt_f32_e32 vcc, s33, v136
	s_waitcnt lgkmcnt(0)
	v_mfma_f32_32x32x16_bf16 v[96:111], v[216:219], v[176:179], v[96:111]
	s_nop 0
	s_waitcnt lgkmcnt(0)
	v_mfma_f32_32x32x16_bf16 v[80:95], v[220:223], v[176:179], v[80:95]
	v_add_f32_e64 v130, v184, 0
	v_add_f32_e64 v131, v185, 0
	v_add_f32_e64 v130, v186, v130
	v_add_f32_e64 v131, v187, v131
	v_add_f32_e64 v130, v188, v130
	v_add_f32_e64 v131, v189, v131
	v_pk_add_f32 v[176:177], v[134:135], v[130:131]
	v_pk_fma_f32 v[130:131], v[136:137], s[96:97], v[12:13] op_sel_hi:[1,0,0]
	s_nop 0
	v_exp_f32_e32 v130, v130
	v_exp_f32_e32 v131, v131
	v_cndmask_b32_e32 v132, 0, v130, vcc
	v_cmp_lt_f32_e32 vcc, s33, v137
	v_cndmask_b32_e64 v178, v130, v132, s[8:9]
	s_nop 0
	v_cndmask_b32_e32 v133, 0, v131, vcc
	v_cndmask_b32_e64 v179, v131, v133, s[8:9]
	v_pk_fma_f32 v[132:133], v[138:139], s[96:97], v[12:13] op_sel_hi:[1,0,0]
	v_cmp_lt_f32_e32 vcc, s33, v138
	v_exp_f32_e32 v131, v132
	v_exp_f32_e32 v132, v133
	v_cvt_pk_bf16_f32 v130, v178, v179
	v_cndmask_b32_e32 v133, 0, v131, vcc
	v_cmp_lt_f32_e32 vcc, s33, v139
	v_cndmask_b32_e64 v138, v131, v133, s[8:9]
	s_nop 0
	v_cndmask_b32_e32 v134, 0, v132, vcc
	v_cndmask_b32_e64 v139, v132, v134, s[8:9]
	v_pk_fma_f32 v[132:133], v[140:141], s[96:97], v[12:13] op_sel_hi:[1,0,0]
	v_cmp_lt_f32_e32 vcc, s33, v140
	v_exp_f32_e32 v132, v132
	v_exp_f32_e32 v133, v133
	v_cvt_pk_bf16_f32 v131, v138, v139
	v_cndmask_b32_e32 v134, 0, v132, vcc
	v_cmp_lt_f32_e32 vcc, s33, v141
	v_cndmask_b32_e64 v140, v132, v134, s[8:9]
	s_nop 0
	v_cndmask_b32_e32 v135, 0, v133, vcc
	v_cndmask_b32_e64 v141, v133, v135, s[8:9]
	v_pk_fma_f32 v[134:135], v[142:143], s[96:97], v[12:13] op_sel_hi:[1,0,0]
	v_cmp_lt_f32_e32 vcc, s33, v142
	v_exp_f32_e32 v133, v134
	v_exp_f32_e32 v134, v135
	v_cvt_pk_bf16_f32 v132, v140, v141
	v_cndmask_b32_e32 v135, 0, v133, vcc
	v_cmp_lt_f32_e32 vcc, s33, v143
	v_cndmask_b32_e64 v142, v133, v135, s[8:9]
	s_nop 0
	v_cndmask_b32_e32 v136, 0, v134, vcc
	v_cndmask_b32_e64 v143, v134, v136, s[8:9]
	s_nop 0
	v_cvt_pk_bf16_f32 v133, v142, v143
	v_cmp_lt_f32_e32 vcc, s33, v112
	s_nop 0
	v_mfma_f32_32x32x16_bf16 v[96:111], v[224:227], v[130:133], v[96:111]
	v_mfma_f32_32x32x16_bf16 v[80:95], v[228:231], v[130:133], v[80:95]
	v_fma_f32 v132, v112, s96, v12
	v_fma_f32 v133, v113, s96, v12
	v_fma_f32 v134, v114, s96, v12
	v_fma_f32 v135, v115, s96, v12
	v_exp_f32_e32 v132, v132
	v_exp_f32_e32 v133, v133
	v_pk_add_f32 v[130:131], v[178:179], v[176:177]
	v_cndmask_b32_e32 v112, 0, v132, vcc
	v_cmp_lt_f32_e32 vcc, s33, v113
	v_pk_add_f32 v[130:131], v[138:139], v[130:131]
	v_cndmask_b32_e64 v132, v132, v112, s[8:9]
	v_cndmask_b32_e32 v113, 0, v133, vcc
	v_cndmask_b32_e64 v133, v133, v113, s[8:9]
	v_exp_f32_e32 v113, v134
	v_exp_f32_e32 v134, v135
	v_cmp_lt_f32_e32 vcc, s33, v114
	v_cvt_pk_bf16_f32 v112, v132, v133
	v_pk_add_f32 v[130:131], v[140:141], v[130:131]
	v_cndmask_b32_e32 v114, 0, v113, vcc
	v_cmp_lt_f32_e32 vcc, s33, v115
	v_pk_add_f32 v[130:131], v[142:143], v[130:131]
	s_nop 0
	v_cndmask_b32_e32 v115, 0, v134, vcc
	v_cndmask_b32_e64 v135, v134, v115, s[8:9]
	v_cndmask_b32_e64 v134, v113, v114, s[8:9]
	v_pk_fma_f32 v[114:115], v[116:117], s[96:97], v[12:13] op_sel_hi:[1,0,0]
	v_cmp_lt_f32_e32 vcc, s33, v116
	v_exp_f32_e32 v114, v114
	v_exp_f32_e32 v115, v115
	v_cvt_pk_bf16_f32 v113, v134, v135
	v_cndmask_b32_e32 v116, 0, v114, vcc
	v_cmp_lt_f32_e32 vcc, s33, v117
	v_cndmask_b32_e64 v136, v114, v116, s[8:9]
	s_nop 0
	v_cndmask_b32_e32 v117, 0, v115, vcc
	v_cndmask_b32_e64 v137, v115, v117, s[8:9]
	v_pk_fma_f32 v[116:117], v[118:119], s[96:97], v[12:13] op_sel_hi:[1,0,0]
	v_cmp_lt_f32_e32 vcc, s33, v118
	v_exp_f32_e32 v115, v116
	v_exp_f32_e32 v116, v117
	v_cvt_pk_bf16_f32 v114, v136, v137
	v_cndmask_b32_e32 v117, 0, v115, vcc
	v_cmp_lt_f32_e32 vcc, s33, v119
	v_cndmask_b32_e64 v138, v115, v117, s[8:9]
	s_nop 0
	v_cndmask_b32_e32 v118, 0, v116, vcc
	v_cndmask_b32_e64 v139, v116, v118, s[8:9]
	s_nop 0
	v_cvt_pk_bf16_f32 v115, v138, v139
	v_cmp_lt_f32_e32 vcc, s33, v120
	s_waitcnt lgkmcnt(0)
; #define MFMA(a, b, c) __builtin_amdgcn_mfma_f32_32x32x16_bf16((a), (b), (c), 0, 0, 0)
;     ...
;         rs2 += pv;
;         pf.u[j] = __builtin_bit_cast(unsigned, __builtin_convertvector(pv, hwbf16x2));
;       }
; #pragma unroll
;       for (int d = 0; d < DV / 32; ++d) {
;         const char* vp = base + C::KBYTES + (d * 32 + lr) * C::VSTR + (ks * 32 + 16 * st + 4 * lh) * 2;
;         const s16x4 lo = *(const s16x4*)vp, hi = *(const s16x4*)(vp + 16);
;         const bf16x8 vf = __builtin_shufflevector(lo, hi, 0, 1, 2, 3, 4, 5, 6, 7);
;         O[d] = MFMA(vf, pf.v, O[d]);
;       }
;     }
;   float rs = rs2.x + rs2.y;
;   rs += __shfl_xor(rs, 32);
;   l += rs;
;     ...
;     if (t + NST - 1 < ntile) {
;       const int sn = (stage == 0) ? NST - 1 : stage - 1;
;       FA_ISSUE(t + NST - 1, sn)
;     }
	v_mfma_f32_32x32x16_bf16 v[96:111], v[232:235], v[112:115], v[96:111]
	s_nop 0
	s_waitcnt lgkmcnt(0)
	v_mfma_f32_32x32x16_bf16 v[80:95], v[236:239], v[112:115], v[80:95]
	v_add_f32_e64 v112, v132, v130
	v_add_f32_e64 v113, v133, v131
	v_add_f32_e64 v112, v134, v112
	v_add_f32_e64 v113, v135, v113
	v_add_f32_e64 v112, v136, v112
	v_add_f32_e64 v113, v137, v113
	v_pk_add_f32 v[130:131], v[138:139], v[112:113]
	v_pk_fma_f32 v[112:113], v[120:121], s[96:97], v[12:13] op_sel_hi:[1,0,0]
	s_nop 0
	v_exp_f32_e32 v112, v112
	v_exp_f32_e32 v113, v113
	v_cndmask_b32_e32 v114, 0, v112, vcc
	v_cmp_lt_f32_e32 vcc, s33, v121
	v_cndmask_b32_e64 v120, v112, v114, s[8:9]
	s_nop 0
	v_cndmask_b32_e32 v115, 0, v113, vcc
	v_cndmask_b32_e64 v121, v113, v115, s[8:9]
	v_pk_fma_f32 v[114:115], v[122:123], s[96:97], v[12:13] op_sel_hi:[1,0,0]
	v_cmp_lt_f32_e32 vcc, s33, v122
	v_exp_f32_e32 v113, v114
	v_exp_f32_e32 v114, v115
	v_cvt_pk_bf16_f32 v112, v120, v121
	v_cndmask_b32_e32 v115, 0, v113, vcc
	v_cmp_lt_f32_e32 vcc, s33, v123
	v_cndmask_b32_e64 v122, v113, v115, s[8:9]
	s_nop 0
	v_cndmask_b32_e32 v116, 0, v114, vcc
	v_cndmask_b32_e64 v123, v114, v116, s[8:9]
	v_pk_fma_f32 v[114:115], v[124:125], s[96:97], v[12:13] op_sel_hi:[1,0,0]
	v_cmp_lt_f32_e32 vcc, s33, v124
	v_exp_f32_e32 v114, v114
	v_exp_f32_e32 v115, v115
	v_cvt_pk_bf16_f32 v113, v122, v123
	v_cndmask_b32_e32 v116, 0, v114, vcc
	v_cmp_lt_f32_e32 vcc, s33, v125
	v_cndmask_b32_e64 v124, v114, v116, s[8:9]
	s_nop 0
	v_cndmask_b32_e32 v117, 0, v115, vcc
	v_cndmask_b32_e64 v125, v115, v117, s[8:9]
	v_pk_fma_f32 v[116:117], v[126:127], s[96:97], v[12:13] op_sel_hi:[1,0,0]
	v_cmp_lt_f32_e32 vcc, s33, v126
	v_exp_f32_e32 v12, v116
	v_exp_f32_e32 v115, v117
	v_cvt_pk_bf16_f32 v114, v124, v125
	v_cndmask_b32_e32 v116, 0, v12, vcc
	v_cmp_lt_f32_e32 vcc, s33, v127
	v_cndmask_b32_e64 v126, v12, v116, s[8:9]
	s_nop 0
	v_cndmask_b32_e32 v117, 0, v115, vcc
	v_cndmask_b32_e64 v127, v115, v117, s[8:9]
	s_nop 0
	v_cvt_pk_bf16_f32 v115, v126, v127
	s_nop 1
	v_mfma_f32_32x32x16_bf16 v[96:111], v[240:243], v[112:115], v[96:111]
	s_nop 0
	s_waitcnt lgkmcnt(0)
	v_mfma_f32_32x32x16_bf16 v[80:95], v[244:247], v[112:115], v[80:95]
	v_add_f32_e64 v112, v120, v130
	v_add_f32_e64 v113, v121, v131
	v_add_f32_e64 v112, v122, v112
	v_add_f32_e64 v113, v123, v113
	v_add_f32_e64 v112, v124, v112
	v_add_f32_e64 v113, v125, v113
	v_pk_add_f32 v[112:113], v[126:127], v[112:113]
	s_nop 0
	v_add_f32_e32 v12, v112, v113
	ds_bpermute_b32 v112, v165, v12
	s_cmp_ge_i32 s21, s16
	s_cbranch_scc1 .Ldma_m_win2
	s_add_i32 s98, s0, 0xffffb800
	s_cmp_lg_u32 s22, 0
	s_cselect_b32 s98, s98, 0xd800
	s_add_i32 s98, s98, 0
	v_add_u32_e32 v247, s98, v15
	s_nop 0
	v_readfirstlane_b32 s99, v247
	v_add_u32_e32 v247, s98, v13
	s_mov_b32 m0, s99
	v_readfirstlane_b32 s99, v247
	v_add_u32_e32 v247, s98, v169
	global_load_lds_dwordx4 v[10:11], off
	s_mov_b32 m0, s99
	v_readfirstlane_b32 s98, v247
	global_load_lds_dwordx4 v[8:9], off
	s_mov_b32 m0, s98
	s_nop 0
	global_load_lds_dwordx4 v[6:7], off

; #define MFMA(a, b, c) __builtin_amdgcn_mfma_f32_32x32x16_bf16((a), (b), (c), 0, 0, 0)
;     ...
;   float mc = m * c2;
;   if (MODE == 2) mc = selbit ? mc : 1e30f;
;   const f32x2v c2v = {c2, c2}, mcv = {-mc, -mc};
;   f32x2v rs2 = {0.f, 0.f};
; #pragma unroll
;   for (int ks = 0; ks < 2; ++ks)
; #pragma unroll
;     for (int st = 0; st < 2; ++st) {
;       union { unsigned u[4]; bf16x8 v; } pf;
; #pragma unroll
;       for (int j = 0; j < 4; ++j) {
;         const int i0 = 8 * st + 2 * j;
;         f32x2v t = {S[ks][i0], S[ks][i0 + 1]};
;         t = __builtin_elementwise_fma(t, c2v, mcv);
;         f32x2v pv;
;         if (variant == 1) { pv = t; } else {
;         pv.x = __builtin_amdgcn_exp2f(t.x);
;         pv.y = __builtin_amdgcn_exp2f(t.y);
;         }
;         if (MODE != 0) {
;           if (need_mask) {
;             pv.x = (S[ks][i0] > -1e29f) ? pv.x : 0.f;
;             pv.y = (S[ks][i0 + 1] > -1e29f) ? pv.y : 0.f;
;           }
;         }
;         rs2 += pv;
;         pf.u[j] = __builtin_bit_cast(unsigned, __builtin_convertvector(pv, hwbf16x2));
;       }
; #pragma unroll
;       for (int d = 0; d < DV / 32; ++d) {
;         const char* vp = base + C::KBYTES + (d * 32 + lr) * C::VSTR + (ks * 32 + 16 * st + 4 * lh) * 2;
;         const s16x4 lo = *(const s16x4*)vp, hi = *(const s16x4*)(vp + 16);
;         const bf16x8 vf = __builtin_shufflevector(lo, hi, 0, 1, 2, 3, 4, 5, 6, 7);
;         O[d] = MFMA(vf, pf.v, O[d]);
;       }
;     }
;   float rs = rs2.x + rs2.y;
;   rs += __shfl_xor(rs, 32);
;   l += rs;
;     ...
;     if (t + NST - 1 < ntile) {
;       const int sn = (stage == 0) ? NST - 1 : stage - 1;
;       FA_ISSUE(t + NST - 1, sn)
;     }
.Lfast_win2:
	v_mul_f32_e32 v12, 0xbe38aa3b, v12
	v_pk_fma_f32 v[176:177], v[128:129], s[96:97], v[12:13] op_sel_hi:[1,0,0]
	v_exp_f32_e32 v184, v176
	v_exp_f32_e32 v185, v177
	v_pk_fma_f32 v[128:129], v[130:131], s[96:97], v[12:13] op_sel_hi:[1,0,0]
	v_exp_f32_e32 v186, v128
	v_exp_f32_e32 v187, v129
	v_cvt_pk_bf16_f32 v176, v184, v185
	v_pk_fma_f32 v[128:129], v[132:133], s[96:97], v[12:13] op_sel_hi:[1,0,0]
	v_exp_f32_e32 v188, v128
	v_exp_f32_e32 v189, v129
	v_cvt_pk_bf16_f32 v177, v186, v187
	v_pk_fma_f32 v[128:129], v[134:135], s[96:97], v[12:13] op_sel_hi:[1,0,0]
	v_exp_f32_e32 v134, v128
	v_exp_f32_e32 v135, v129
	v_cvt_pk_bf16_f32 v178, v188, v189
	v_cvt_pk_bf16_f32 v179, v134, v135
	s_waitcnt lgkmcnt(0)
	s_nop 0
	v_mfma_f32_32x32x16_bf16 v[96:111], v[216:219], v[176:179], v[96:111]
	v_mfma_f32_32x32x16_bf16 v[80:95], v[220:223], v[176:179], v[80:95]
	v_add_f32_e64 v130, v184, 0
	v_add_f32_e64 v131, v185, 0
	v_add_f32_e64 v130, v186, v130
	v_add_f32_e64 v131, v187, v131
	v_add_f32_e64 v130, v188, v130
	v_add_f32_e64 v131, v189, v131
	v_pk_add_f32 v[176:177], v[134:135], v[130:131]
	v_pk_fma_f32 v[130:131], v[136:137], s[96:97], v[12:13] op_sel_hi:[1,0,0]
	v_exp_f32_e32 v178, v130
	v_exp_f32_e32 v179, v131
	v_pk_fma_f32 v[132:133], v[138:139], s[96:97], v[12:13] op_sel_hi:[1,0,0]
	v_exp_f32_e32 v138, v132
	v_exp_f32_e32 v139, v133
	v_cvt_pk_bf16_f32 v130, v178, v179
	v_pk_fma_f32 v[132:133], v[140:141], s[96:97], v[12:13] op_sel_hi:[1,0,0]
	v_exp_f32_e32 v140, v132
	v_exp_f32_e32 v141, v133
	v_cvt_pk_bf16_f32 v131, v138, v139
	v_pk_fma_f32 v[134:135], v[142:143], s[96:97], v[12:13] op_sel_hi:[1,0,0]
	v_exp_f32_e32 v142, v134
	v_exp_f32_e32 v143, v135
	v_cvt_pk_bf16_f32 v132, v140, v141
	v_cvt_pk_bf16_f32 v133, v142, v143
	s_nop 1
	v_mfma_f32_32x32x16_bf16 v[96:111], v[224:227], v[130:133], v[96:111]
	v_mfma_f32_32x32x16_bf16 v[80:95], v[228:231], v[130:133], v[80:95]
	v_fma_f32 v132, v112, s96, v12
	v_fma_f32 v133, v113, s96, v12
	v_fma_f32 v134, v114, s96, v12
	v_fma_f32 v135, v115, s96, v12
	v_exp_f32_e32 v132, v132
	v_exp_f32_e32 v133, v133
	v_pk_add_f32 v[130:131], v[178:179], v[176:177]
	v_pk_add_f32 v[130:131], v[138:139], v[130:131]
	v_exp_f32_e32 v134, v134
	v_exp_f32_e32 v135, v135
	v_cvt_pk_bf16_f32 v112, v132, v133
	v_pk_add_f32 v[130:131], v[140:141], v[130:131]
	v_pk_add_f32 v[130:131], v[142:143], v[130:131]
	v_pk_fma_f32 v[114:115], v[116:117], s[96:97], v[12:13] op_sel_hi:[1,0,0]
	v_exp_f32_e32 v136, v114
	v_exp_f32_e32 v137, v115
	v_cvt_pk_bf16_f32 v113, v134, v135
	v_pk_fma_f32 v[116:117], v[118:119], s[96:97], v[12:13] op_sel_hi:[1,0,0]
	v_exp_f32_e32 v138, v116
	v_exp_f32_e32 v139, v117
	v_cvt_pk_bf16_f32 v114, v136, v137
	v_cvt_pk_bf16_f32 v115, v138, v139
	s_nop 1
	v_mfma_f32_32x32x16_bf16 v[96:111], v[232:235], v[112:115], v[96:111]
	v_mfma_f32_32x32x16_bf16 v[80:95], v[236:239], v[112:115], v[80:95]
	v_add_f32_e64 v112, v132, v130
	v_add_f32_e64 v113, v133, v131
	v_add_f32_e64 v112, v134, v112
	v_add_f32_e64 v113, v135, v113
	v_add_f32_e64 v112, v136, v112
	v_add_f32_e64 v113, v137, v113
	v_pk_add_f32 v[130:131], v[138:139], v[112:113]
	v_pk_fma_f32 v[112:113], v[120:121], s[96:97], v[12:13] op_sel_hi:[1,0,0]
	v_exp_f32_e32 v120, v112
	v_exp_f32_e32 v121, v113
	v_pk_fma_f32 v[114:115], v[122:123], s[96:97], v[12:13] op_sel_hi:[1,0,0]
	v_exp_f32_e32 v122, v114
	v_exp_f32_e32 v123, v115
	v_cvt_pk_bf16_f32 v112, v120, v121
	v_pk_fma_f32 v[114:115], v[124:125], s[96:97], v[12:13] op_sel_hi:[1,0,0]
	v_exp_f32_e32 v124, v114
	v_exp_f32_e32 v125, v115
	v_cvt_pk_bf16_f32 v113, v122, v123
	v_pk_fma_f32 v[116:117], v[126:127], s[96:97], v[12:13] op_sel_hi:[1,0,0]
	v_exp_f32_e32 v126, v116
	v_exp_f32_e32 v127, v117
	v_cvt_pk_bf16_f32 v114, v124, v125
	v_cvt_pk_bf16_f32 v115, v126, v127
	s_nop 1
	v_mfma_f32_32x32x16_bf16 v[96:111], v[240:243], v[112:115], v[96:111]
	v_mfma_f32_32x32x16_bf16 v[80:95], v[244:247], v[112:115], v[80:95]
	v_add_f32_e64 v112, v120, v130
	v_add_f32_e64 v113, v121, v131
	v_add_f32_e64 v112, v122, v112
	v_add_f32_e64 v113, v123, v113
	v_add_f32_e64 v112, v124, v112
	v_add_f32_e64 v113, v125, v113
	v_pk_add_f32 v[112:113], v[126:127], v[112:113]
	v_add_f32_e32 v12, v112, v113
	ds_bpermute_b32 v112, v165, v12
	s_cmp_ge_i32 s21, s16
	s_cbranch_scc1 .Ldma_f_win2
	s_add_i32 s98, s0, 0xffffb800
	s_cmp_lg_u32 s22, 0
	s_cselect_b32 s98, s98, 0xd800
	s_add_i32 s98, s98, 0
	v_add_u32_e32 v247, s98, v15
	s_nop 0
	v_readfirstlane_b32 s99, v247
	v_add_u32_e32 v247, s98, v13
	s_mov_b32 m0, s99
	v_readfirstlane_b32 s99, v247
	v_add_u32_e32 v247, s98, v169
	global_load_lds_dwordx4 v[10:11], off
	s_mov_b32 m0, s99
	v_readfirstlane_b32 s98, v247
	global_load_lds_dwordx4 v[8:9], off
	s_mov_b32 m0, s98
	s_nop 0
	global_load_lds_dwordx4 v[6:7], off
